# chains ordered as snake over (m,n) with alternating k order so each chain boundary shares one MFMA source operand
# speedup vs baseline: 1.0209x; 1.0085x over previous
; #define PG8_STAGE(bufoff, gbase, voff) do { _Pragma("unroll") for (int _i = 0; _i < 2; ++_i) \
;         __builtin_amdgcn_global_load_lds((const unsigned*)((const char*)(gbase) + (voff)[_i]), (PG8_LAS unsigned*)(lds + (bufoff) + ldsw + _i * 8192), 16, 0, 0); } while (0)
; #define PG8_LDA(dst, b, h) do { _Pragma("unroll") for (int m = 0; m < 4; ++m) _Pragma("unroll") for (int k = 0; k < 2; ++k) dst[m][k] = *(const PG8_LAS bf16x8*)(lds + PG8_SA(b, h) + aoff + m * 2048 + k * 1024); } while (0)
; #define PG8_LDB(dst, b, h) do { _Pragma("unroll") for (int n = 0; n < 2; ++n) _Pragma("unroll") for (int k = 0; k < 2; ++k) dst[n][k] = *(const PG8_LAS bf16x8*)(lds + PG8_SB(b, h) + boff + n * 2048 + k * 1024); } while (0)
; #define PG8_MMA(ai, bj, At, Bt) do { __builtin_amdgcn_s_setprio(1); _Pragma("unroll") for (int m = 0; m < 4; ++m) _Pragma("unroll") for (int n = 0; n < 2; ++n) _Pragma("unroll") for (int k = 0; k < 2; ++k) \
;         acc[ai][bj][m][n] = __builtin_amdgcn_mfma_f32_16x16x32_bf16(Bt[n][k], At[m][k], acc[ai][bj][m][n], 0, 0, 0); __builtin_amdgcn_s_setprio(0); } while (0)
; #define PG8_WAIT_V(n) asm volatile("s_waitcnt vmcnt(" #n ")" ::: "memory")
; template <class Epi, class Sched, bool ALIGN_EPI = false, bool SP2 = false, bool ABLK = false, bool BBLK = false>
; __device__ __forceinline__ void gemm_phase(PG8_LAS unsigned char* lds, const Gemm g, const Sched& S, const Epi& E) {
;     ...
;         for (int t = 0; t < nt; t += 2) {
;             const bool last = (t == nt - 2);
;             const char* a1 = cA + (size_t)(t + 1) * kstepA;
;             const char* a2 = last ? nA : cA + (size_t)(t + 2) * kstepA; const char* b2 = last ? nB : cB + (size_t)(t + 2) * kstepB;
;             const char* a3 = a2 + kstepA; const char* b3 = b2 + kstepB;
;             if (last && has_next) S.a_ready(nxt);
;             if constexpr (SP2) {
;             PG8_LDB(B0, 0, 0); PG8_LDB(B1, 0, 1); PG8_SCHED; PG8_LDA(At, 0, 0); PG8_STAGE(PG8_SA(1, 1), a1 + hstepA, voffA);
;             PG8_WAIT_V(8); PG8_WAIT_L(0); PG8_BAR; PG8_MMA(0, 0, At, B0); PG8_MMA(0, 1, At, B1); PG8_BAR; PG8_SCHED;
;             PG8_LDA(At, 0, 1); PG8_STAGE(PG8_SB(0, 0), b2, voffB); PG8_STAGE(PG8_SB(0, 1), b2 + hstepB, voffB); PG8_STAGE(PG8_SA(0, 0), a2, voffA);
;             PG8_WAIT_V(8); PG8_WAIT_L(0); PG8_BAR; PG8_MMA(1, 0, At, B0); PG8_MMA(1, 1, At, B1); PG8_BAR; PG8_SCHED;
.LBB0_185:
	s_add_u32 s13, s20, 0x4000
	s_addc_u32 s22, s21, 0
	s_cmp_eq_u32 vcc_hi, 28
	s_cselect_b32 s26, s70, s13
	s_cselect_b32 s27, s9, s22
	s_cselect_b32 s24, s71, s77
	s_cselect_b32 s25, s7, vcc_lo
	s_add_u32 s22, s26, 0x8000
	s_addc_u32 s23, s27, 0
	s_add_i32 s13, 0, 0x10000
	v_add_u32_e32 v36, s13, v160
	s_add_i32 s88, 0, 0x14000
	ds_read_b128 v[152:155], v36
	ds_read_b128 v[156:159], v36 offset:1024
	ds_read_b128 v[162:165], v36 offset:2048
	ds_read_b128 v[166:169], v36 offset:3072
	v_add_u32_e32 v36, s88, v160
	ds_read_b128 v[170:173], v36
	ds_read_b128 v[174:177], v36 offset:1024
	ds_read_b128 v[178:181], v36 offset:2048
	ds_read_b128 v[182:185], v36 offset:3072
	s_add_i32 m0, s19, 0xc000
	ds_read_b128 v[186:189], v161
	ds_read_b128 v[190:193], v161 offset:1024
	ds_read_b128 v[194:197], v161 offset:2048
	ds_read_b128 v[198:201], v161 offset:3072
	ds_read_b128 v[202:205], v161 offset:4096
	ds_read_b128 v[206:209], v161 offset:5120
	ds_read_b128 v[210:213], v161 offset:6144
	ds_read_b128 v[214:217], v161 offset:7168
	global_load_lds_dwordx4 v148, s[20:21]
	s_add_i32 m0, s19, 0xe000
	s_nop 0
	global_load_lds_dwordx4 v150, s[20:21]
	s_waitcnt vmcnt(8)
	s_waitcnt lgkmcnt(0)
	v_mfma_f32_16x16x32_bf16 v[132:135], v[152:155], v[186:189], v[132:135]
	v_mfma_f32_16x16x32_bf16 v[132:135], v[156:159], v[190:193], v[132:135]
	v_mfma_f32_16x16x32_bf16 v[128:131], v[166:169], v[190:193], v[128:131]
	v_mfma_f32_16x16x32_bf16 v[128:131], v[162:165], v[186:189], v[128:131]
	s_barrier
	s_setprio 1
	v_mfma_f32_16x16x32_bf16 v[112:115], v[162:165], v[194:197], v[112:115]
	v_mfma_f32_16x16x32_bf16 v[112:115], v[166:169], v[198:201], v[112:115]
	v_mfma_f32_16x16x32_bf16 v[116:119], v[156:159], v[198:201], v[116:119]
	v_mfma_f32_16x16x32_bf16 v[116:119], v[152:155], v[194:197], v[116:119]
	v_mfma_f32_16x16x32_bf16 v[100:103], v[152:155], v[202:205], v[100:103]
	v_mfma_f32_16x16x32_bf16 v[100:103], v[156:159], v[206:209], v[100:103]
	v_mfma_f32_16x16x32_bf16 v[96:99], v[166:169], v[206:209], v[96:99]
	v_mfma_f32_16x16x32_bf16 v[96:99], v[162:165], v[202:205], v[96:99]
	v_mfma_f32_16x16x32_bf16 v[80:83], v[162:165], v[210:213], v[80:83]
	v_mfma_f32_16x16x32_bf16 v[80:83], v[166:169], v[214:217], v[80:83]
	v_mfma_f32_16x16x32_bf16 v[84:87], v[156:159], v[214:217], v[84:87]
	v_mfma_f32_16x16x32_bf16 v[84:87], v[152:155], v[210:213], v[84:87]
	s_setprio 0
	s_setprio 1
	v_mfma_f32_16x16x32_bf16 v[124:127], v[170:173], v[186:189], v[124:127]
	v_mfma_f32_16x16x32_bf16 v[124:127], v[174:177], v[190:193], v[124:127]
	v_mfma_f32_16x16x32_bf16 v[120:123], v[182:185], v[190:193], v[120:123]
	v_mfma_f32_16x16x32_bf16 v[120:123], v[178:181], v[186:189], v[120:123]
	v_mfma_f32_16x16x32_bf16 v[104:107], v[178:181], v[194:197], v[104:107]
	v_mfma_f32_16x16x32_bf16 v[104:107], v[182:185], v[198:201], v[104:107]
	v_mfma_f32_16x16x32_bf16 v[108:111], v[174:177], v[198:201], v[108:111]
	v_mfma_f32_16x16x32_bf16 v[108:111], v[170:173], v[194:197], v[108:111]
	v_mfma_f32_16x16x32_bf16 v[92:95], v[170:173], v[202:205], v[92:95]
	v_mfma_f32_16x16x32_bf16 v[92:95], v[174:177], v[206:209], v[92:95]
	v_mfma_f32_16x16x32_bf16 v[88:91], v[182:185], v[206:209], v[88:91]
	v_mfma_f32_16x16x32_bf16 v[88:91], v[178:181], v[202:205], v[88:91]
	v_mfma_f32_16x16x32_bf16 v[72:75], v[178:181], v[210:213], v[72:75]
	v_mfma_f32_16x16x32_bf16 v[72:75], v[182:185], v[214:217], v[72:75]
	v_mfma_f32_16x16x32_bf16 v[76:79], v[174:177], v[214:217], v[76:79]
	v_mfma_f32_16x16x32_bf16 v[76:79], v[170:173], v[210:213], v[76:79]
	s_setprio 0
	s_barrier
	s_add_i32 s13, s13, s31
	s_mov_b32 m0, s13
	ds_read_b128 v[186:189], v161 offset:16384
	ds_read_b128 v[190:193], v161 offset:17408
	ds_read_b128 v[194:197], v161 offset:18432
	ds_read_b128 v[198:201], v161 offset:19456
	ds_read_b128 v[202:205], v161 offset:20480
	ds_read_b128 v[206:209], v161 offset:21504
	ds_read_b128 v[210:213], v161 offset:22528
	ds_read_b128 v[214:217], v161 offset:23552
	global_load_lds_dwordx4 v140, s[24:25]
	s_add_i32 m0, s13, 0x2000
	s_add_u32 s68, s24, 0x4000
	s_addc_u32 s69, s25, 0
	s_add_i32 s13, s88, s31
	global_load_lds_dwordx4 v136, s[24:25]
	s_mov_b32 m0, s13
	s_nop 0
	global_load_lds_dwordx4 v140, s[68:69]
	s_add_i32 m0, s13, 0x2000
	s_nop 0
	global_load_lds_dwordx4 v136, s[68:69]
	s_mov_b32 m0, s19
	s_nop 0
	global_load_lds_dwordx4 v142, s[26:27]
	s_mov_b32 m0, s35
	s_nop 0
	global_load_lds_dwordx4 v138, s[26:27]
	s_waitcnt vmcnt(8)
	s_waitcnt lgkmcnt(0)
	v_mfma_f32_16x16x32_bf16 v[68:71], v[152:155], v[186:189], v[68:71]
	v_mfma_f32_16x16x32_bf16 v[68:71], v[156:159], v[190:193], v[68:71]
	v_mfma_f32_16x16x32_bf16 v[64:67], v[166:169], v[190:193], v[64:67]
	v_mfma_f32_16x16x32_bf16 v[64:67], v[162:165], v[186:189], v[64:67]
	s_barrier
; #define PG8_STAGE(bufoff, gbase, voff) do { _Pragma("unroll") for (int _i = 0; _i < 2; ++_i) \
;         __builtin_amdgcn_global_load_lds((const unsigned*)((const char*)(gbase) + (voff)[_i]), (PG8_LAS unsigned*)(lds + (bufoff) + ldsw + _i * 8192), 16, 0, 0); } while (0)
; #define PG8_LDA(dst, b, h) do { _Pragma("unroll") for (int m = 0; m < 4; ++m) _Pragma("unroll") for (int k = 0; k < 2; ++k) dst[m][k] = *(const PG8_LAS bf16x8*)(lds + PG8_SA(b, h) + aoff + m * 2048 + k * 1024); } while (0)
; #define PG8_LDB(dst, b, h) do { _Pragma("unroll") for (int n = 0; n < 2; ++n) _Pragma("unroll") for (int k = 0; k < 2; ++k) dst[n][k] = *(const PG8_LAS bf16x8*)(lds + PG8_SB(b, h) + boff + n * 2048 + k * 1024); } while (0)
; #define PG8_MMA(ai, bj, At, Bt) do { __builtin_amdgcn_s_setprio(1); _Pragma("unroll") for (int m = 0; m < 4; ++m) _Pragma("unroll") for (int n = 0; n < 2; ++n) _Pragma("unroll") for (int k = 0; k < 2; ++k) \
;         acc[ai][bj][m][n] = __builtin_amdgcn_mfma_f32_16x16x32_bf16(Bt[n][k], At[m][k], acc[ai][bj][m][n], 0, 0, 0); __builtin_amdgcn_s_setprio(0); } while (0)
; #define PG8_WAIT_V(n) asm volatile("s_waitcnt vmcnt(" #n ")" ::: "memory")
; #define PG8_WAIT_L(n) asm volatile("s_waitcnt lgkmcnt(" #n ")" ::: "memory")
; #define PG8_BAR __builtin_amdgcn_s_barrier()
; #define PG8_SCHED __builtin_amdgcn_sched_barrier(0)
; template <class Epi, class Sched, bool ALIGN_EPI = false, bool SP2 = false, bool ABLK = false, bool BBLK = false>
; __device__ __forceinline__ void gemm_phase(PG8_LAS unsigned char* lds, const Gemm g, const Sched& S, const Epi& E) {
;     ...
;             PG8_WAIT_V(8); PG8_WAIT_L(0); PG8_BAR; PG8_MMA(1, 0, At, B0); PG8_MMA(1, 1, At, B1); PG8_BAR; PG8_SCHED;
;             PG8_LDB(B0, 1, 0); PG8_LDB(B1, 1, 1); PG8_SCHED; PG8_LDA(At, 1, 0); PG8_STAGE(PG8_SA(0, 1), a2 + hstepA, voffA);
;             PG8_WAIT_V(8); PG8_WAIT_L(0); PG8_BAR; PG8_MMA(0, 0, At, B0); PG8_MMA(0, 1, At, B1); PG8_BAR; PG8_SCHED;
;             PG8_LDA(At, 1, 1); PG8_STAGE(PG8_SB(1, 0), b3, voffB); PG8_STAGE(PG8_SB(1, 1), b3 + hstepB, voffB); PG8_STAGE(PG8_SA(1, 0), a3, voffA);
;             PG8_WAIT_V(8); PG8_WAIT_L(0); PG8_BAR; PG8_MMA(1, 0, At, B0); PG8_MMA(1, 1, At, B1); PG8_BAR; PG8_SCHED;
	s_setprio 1
	v_mfma_f32_16x16x32_bf16 v[48:51], v[162:165], v[194:197], v[48:51]
	v_mfma_f32_16x16x32_bf16 v[48:51], v[166:169], v[198:201], v[48:51]
	v_mfma_f32_16x16x32_bf16 v[52:55], v[156:159], v[198:201], v[52:55]
	v_mfma_f32_16x16x32_bf16 v[52:55], v[152:155], v[194:197], v[52:55]
	v_mfma_f32_16x16x32_bf16 v[32:35], v[152:155], v[202:205], v[32:35]
	v_mfma_f32_16x16x32_bf16 v[32:35], v[156:159], v[206:209], v[32:35]
	v_mfma_f32_16x16x32_bf16 v[28:31], v[166:169], v[206:209], v[28:31]
	v_mfma_f32_16x16x32_bf16 v[28:31], v[162:165], v[202:205], v[28:31]
	v_mfma_f32_16x16x32_bf16 v[12:15], v[162:165], v[210:213], v[12:15]
	v_mfma_f32_16x16x32_bf16 v[12:15], v[166:169], v[214:217], v[12:15]
	v_mfma_f32_16x16x32_bf16 v[16:19], v[156:159], v[214:217], v[16:19]
	v_mfma_f32_16x16x32_bf16 v[16:19], v[152:155], v[210:213], v[16:19]
	s_setprio 0
	s_setprio 1
	v_mfma_f32_16x16x32_bf16 v[60:63], v[170:173], v[186:189], v[60:63]
	v_mfma_f32_16x16x32_bf16 v[60:63], v[174:177], v[190:193], v[60:63]
	v_mfma_f32_16x16x32_bf16 v[56:59], v[182:185], v[190:193], v[56:59]
	v_mfma_f32_16x16x32_bf16 v[56:59], v[178:181], v[186:189], v[56:59]
	v_mfma_f32_16x16x32_bf16 v[40:43], v[178:181], v[194:197], v[40:43]
	v_mfma_f32_16x16x32_bf16 v[40:43], v[182:185], v[198:201], v[40:43]
	v_mfma_f32_16x16x32_bf16 v[44:47], v[174:177], v[198:201], v[44:47]
	v_mfma_f32_16x16x32_bf16 v[44:47], v[170:173], v[194:197], v[44:47]
	v_mfma_f32_16x16x32_bf16 v[24:27], v[170:173], v[202:205], v[24:27]
	v_mfma_f32_16x16x32_bf16 v[24:27], v[174:177], v[206:209], v[24:27]
	v_mfma_f32_16x16x32_bf16 v[20:23], v[182:185], v[206:209], v[20:23]
	v_mfma_f32_16x16x32_bf16 v[20:23], v[178:181], v[202:205], v[20:23]
	v_mfma_f32_16x16x32_bf16 v[4:7], v[178:181], v[210:213], v[4:7]
	v_mfma_f32_16x16x32_bf16 v[4:7], v[182:185], v[214:217], v[4:7]
	v_mfma_f32_16x16x32_bf16 v[8:11], v[174:177], v[214:217], v[8:11]
	v_mfma_f32_16x16x32_bf16 v[8:11], v[170:173], v[210:213], v[8:11]
	s_setprio 0
	s_barrier
	s_add_i32 s13, 0, 0x18000
	v_add_u32_e32 v36, s13, v160
	s_add_i32 s68, 0, 0x1c000
	ds_read_b128 v[152:155], v36
	ds_read_b128 v[156:159], v36 offset:1024
	ds_read_b128 v[162:165], v36 offset:2048
	ds_read_b128 v[166:169], v36 offset:3072
	v_add_u32_e32 v36, s68, v160
	ds_read_b128 v[170:173], v36
	ds_read_b128 v[174:177], v36 offset:1024
	ds_read_b128 v[178:181], v36 offset:2048
	ds_read_b128 v[182:185], v36 offset:3072
	s_add_u32 s26, s26, 0x4000
	s_addc_u32 s27, s27, 0
	s_mov_b32 m0, s36
	ds_read_b128 v[186:189], v161 offset:32768
	ds_read_b128 v[190:193], v161 offset:33792
	ds_read_b128 v[194:197], v161 offset:34816
	ds_read_b128 v[198:201], v161 offset:35840
	ds_read_b128 v[202:205], v161 offset:36864
	ds_read_b128 v[206:209], v161 offset:37888
	ds_read_b128 v[210:213], v161 offset:38912
	ds_read_b128 v[214:217], v161 offset:39936
	global_load_lds_dwordx4 v142, s[26:27]
	s_mov_b32 m0, s37
	s_nop 0
	global_load_lds_dwordx4 v138, s[26:27]
	s_waitcnt vmcnt(8)
	s_waitcnt lgkmcnt(0)
	v_mfma_f32_16x16x32_bf16 v[132:135], v[152:155], v[186:189], v[132:135]
	v_mfma_f32_16x16x32_bf16 v[132:135], v[156:159], v[190:193], v[132:135]
	v_mfma_f32_16x16x32_bf16 v[128:131], v[166:169], v[190:193], v[128:131]
	v_mfma_f32_16x16x32_bf16 v[128:131], v[162:165], v[186:189], v[128:131]
	s_barrier
	s_setprio 1
	v_mfma_f32_16x16x32_bf16 v[112:115], v[162:165], v[194:197], v[112:115]
	v_mfma_f32_16x16x32_bf16 v[112:115], v[166:169], v[198:201], v[112:115]
	v_mfma_f32_16x16x32_bf16 v[116:119], v[156:159], v[198:201], v[116:119]
	v_mfma_f32_16x16x32_bf16 v[116:119], v[152:155], v[194:197], v[116:119]
	v_mfma_f32_16x16x32_bf16 v[100:103], v[152:155], v[202:205], v[100:103]
	v_mfma_f32_16x16x32_bf16 v[100:103], v[156:159], v[206:209], v[100:103]
	v_mfma_f32_16x16x32_bf16 v[96:99], v[166:169], v[206:209], v[96:99]
	v_mfma_f32_16x16x32_bf16 v[96:99], v[162:165], v[202:205], v[96:99]
	v_mfma_f32_16x16x32_bf16 v[80:83], v[162:165], v[210:213], v[80:83]
	v_mfma_f32_16x16x32_bf16 v[80:83], v[166:169], v[214:217], v[80:83]
	v_mfma_f32_16x16x32_bf16 v[84:87], v[156:159], v[214:217], v[84:87]
	v_mfma_f32_16x16x32_bf16 v[84:87], v[152:155], v[210:213], v[84:87]
	s_setprio 0
	s_setprio 1
	v_mfma_f32_16x16x32_bf16 v[124:127], v[170:173], v[186:189], v[124:127]
	v_mfma_f32_16x16x32_bf16 v[124:127], v[174:177], v[190:193], v[124:127]
	v_mfma_f32_16x16x32_bf16 v[120:123], v[182:185], v[190:193], v[120:123]
	v_mfma_f32_16x16x32_bf16 v[120:123], v[178:181], v[186:189], v[120:123]
	v_mfma_f32_16x16x32_bf16 v[104:107], v[178:181], v[194:197], v[104:107]
	v_mfma_f32_16x16x32_bf16 v[104:107], v[182:185], v[198:201], v[104:107]
	v_mfma_f32_16x16x32_bf16 v[108:111], v[174:177], v[198:201], v[108:111]
	v_mfma_f32_16x16x32_bf16 v[108:111], v[170:173], v[194:197], v[108:111]
	v_mfma_f32_16x16x32_bf16 v[92:95], v[170:173], v[202:205], v[92:95]
	v_mfma_f32_16x16x32_bf16 v[92:95], v[174:177], v[206:209], v[92:95]
	v_mfma_f32_16x16x32_bf16 v[88:91], v[182:185], v[206:209], v[88:91]
	v_mfma_f32_16x16x32_bf16 v[88:91], v[178:181], v[202:205], v[88:91]
	v_mfma_f32_16x16x32_bf16 v[72:75], v[178:181], v[210:213], v[72:75]
	v_mfma_f32_16x16x32_bf16 v[72:75], v[182:185], v[214:217], v[72:75]
	v_mfma_f32_16x16x32_bf16 v[76:79], v[174:177], v[214:217], v[76:79]
	v_mfma_f32_16x16x32_bf16 v[76:79], v[170:173], v[210:213], v[76:79]
	s_setprio 0
	s_barrier
; #define PG8_STAGE(bufoff, gbase, voff) do { _Pragma("unroll") for (int _i = 0; _i < 2; ++_i) \
;         __builtin_amdgcn_global_load_lds((const unsigned*)((const char*)(gbase) + (voff)[_i]), (PG8_LAS unsigned*)(lds + (bufoff) + ldsw + _i * 8192), 16, 0, 0); } while (0)
; #define PG8_LDA(dst, b, h) do { _Pragma("unroll") for (int m = 0; m < 4; ++m) _Pragma("unroll") for (int k = 0; k < 2; ++k) dst[m][k] = *(const PG8_LAS bf16x8*)(lds + PG8_SA(b, h) + aoff + m * 2048 + k * 1024); } while (0)
; #define PG8_MMA(ai, bj, At, Bt) do { __builtin_amdgcn_s_setprio(1); _Pragma("unroll") for (int m = 0; m < 4; ++m) _Pragma("unroll") for (int n = 0; n < 2; ++n) _Pragma("unroll") for (int k = 0; k < 2; ++k) \
;         acc[ai][bj][m][n] = __builtin_amdgcn_mfma_f32_16x16x32_bf16(Bt[n][k], At[m][k], acc[ai][bj][m][n], 0, 0, 0); __builtin_amdgcn_s_setprio(0); } while (0)
; #define PG8_WAIT_V(n) asm volatile("s_waitcnt vmcnt(" #n ")" ::: "memory")
; #define PG8_WAIT_L(n) asm volatile("s_waitcnt lgkmcnt(" #n ")" ::: "memory")
; #define PG8_BAR __builtin_amdgcn_s_barrier()
; #define PG8_SCHED __builtin_amdgcn_sched_barrier(0)
; template <class Epi, class Sched, bool ALIGN_EPI = false, bool SP2 = false, bool ABLK = false, bool BBLK = false>
; __device__ __forceinline__ void gemm_phase(PG8_LAS unsigned char* lds, const Gemm g, const Sched& S, const Epi& E) {
;     ...
;         for (int t = 0; t < nt; t += 2) {
;             const bool last = (t == nt - 2);
;             const char* a1 = cA + (size_t)(t + 1) * kstepA;
;             const char* a2 = last ? nA : cA + (size_t)(t + 2) * kstepA; const char* b2 = last ? nB : cB + (size_t)(t + 2) * kstepB;
;             const char* a3 = a2 + kstepA; const char* b3 = b2 + kstepB;
;     ...
;             PG8_LDA(At, 1, 1); PG8_STAGE(PG8_SB(1, 0), b3, voffB); PG8_STAGE(PG8_SB(1, 1), b3 + hstepB, voffB); PG8_STAGE(PG8_SA(1, 0), a3, voffA);
;             PG8_WAIT_V(8); PG8_WAIT_L(0); PG8_BAR; PG8_MMA(1, 0, At, B0); PG8_MMA(1, 1, At, B1); PG8_BAR; PG8_SCHED;
	s_add_u32 s26, s24, 0x8000
	s_addc_u32 s27, s25, 0
	s_add_i32 s13, s13, s31
	s_mov_b32 m0, s13
	ds_read_b128 v[186:189], v161 offset:49152
	ds_read_b128 v[190:193], v161 offset:50176
	ds_read_b128 v[194:197], v161 offset:51200
	ds_read_b128 v[198:201], v161 offset:52224
	ds_read_b128 v[202:205], v161 offset:53248
	ds_read_b128 v[206:209], v161 offset:54272
	ds_read_b128 v[210:213], v161 offset:55296
	ds_read_b128 v[214:217], v161 offset:56320
	global_load_lds_dwordx4 v140, s[26:27]
	s_add_i32 m0, s13, 0x2000
	s_add_u32 s24, s24, 0xc000
	s_addc_u32 s25, s25, 0
	s_add_i32 s13, s68, s31
	global_load_lds_dwordx4 v136, s[26:27]
	s_mov_b32 m0, s13
	s_nop 0
	global_load_lds_dwordx4 v140, s[24:25]
	s_add_i32 m0, s13, 0x2000
	s_nop 0
	global_load_lds_dwordx4 v136, s[24:25]
	s_mov_b32 m0, s62
	s_nop 0
	global_load_lds_dwordx4 v142, s[22:23]
	s_mov_b32 m0, s63
	s_nop 0
	global_load_lds_dwordx4 v138, s[22:23]
	s_waitcnt vmcnt(8)
	s_waitcnt lgkmcnt(0)
	v_mfma_f32_16x16x32_bf16 v[68:71], v[152:155], v[186:189], v[68:71]
	v_mfma_f32_16x16x32_bf16 v[68:71], v[156:159], v[190:193], v[68:71]
	v_mfma_f32_16x16x32_bf16 v[64:67], v[166:169], v[190:193], v[64:67]
	v_mfma_f32_16x16x32_bf16 v[64:67], v[162:165], v[186:189], v[64:67]
	s_barrier
	s_setprio 1
	v_mfma_f32_16x16x32_bf16 v[48:51], v[162:165], v[194:197], v[48:51]
	v_mfma_f32_16x16x32_bf16 v[48:51], v[166:169], v[198:201], v[48:51]
	v_mfma_f32_16x16x32_bf16 v[52:55], v[156:159], v[198:201], v[52:55]
	v_mfma_f32_16x16x32_bf16 v[52:55], v[152:155], v[194:197], v[52:55]
	v_mfma_f32_16x16x32_bf16 v[32:35], v[152:155], v[202:205], v[32:35]
	v_mfma_f32_16x16x32_bf16 v[32:35], v[156:159], v[206:209], v[32:35]
	v_mfma_f32_16x16x32_bf16 v[28:31], v[166:169], v[206:209], v[28:31]
	v_mfma_f32_16x16x32_bf16 v[28:31], v[162:165], v[202:205], v[28:31]
	v_mfma_f32_16x16x32_bf16 v[12:15], v[162:165], v[210:213], v[12:15]
	v_mfma_f32_16x16x32_bf16 v[12:15], v[166:169], v[214:217], v[12:15]
	v_mfma_f32_16x16x32_bf16 v[16:19], v[156:159], v[214:217], v[16:19]
	v_mfma_f32_16x16x32_bf16 v[16:19], v[152:155], v[210:213], v[16:19]
	s_setprio 0
	s_setprio 1
	v_mfma_f32_16x16x32_bf16 v[60:63], v[170:173], v[186:189], v[60:63]
	v_mfma_f32_16x16x32_bf16 v[60:63], v[174:177], v[190:193], v[60:63]
	v_mfma_f32_16x16x32_bf16 v[56:59], v[182:185], v[190:193], v[56:59]
	v_mfma_f32_16x16x32_bf16 v[56:59], v[178:181], v[186:189], v[56:59]
	v_mfma_f32_16x16x32_bf16 v[40:43], v[178:181], v[194:197], v[40:43]
	v_mfma_f32_16x16x32_bf16 v[40:43], v[182:185], v[198:201], v[40:43]
	v_mfma_f32_16x16x32_bf16 v[44:47], v[174:177], v[198:201], v[44:47]
	v_mfma_f32_16x16x32_bf16 v[44:47], v[170:173], v[194:197], v[44:47]
	v_mfma_f32_16x16x32_bf16 v[24:27], v[170:173], v[202:205], v[24:27]
	v_mfma_f32_16x16x32_bf16 v[24:27], v[174:177], v[206:209], v[24:27]
	v_mfma_f32_16x16x32_bf16 v[20:23], v[182:185], v[206:209], v[20:23]
	v_mfma_f32_16x16x32_bf16 v[20:23], v[178:181], v[202:205], v[20:23]
	v_mfma_f32_16x16x32_bf16 v[4:7], v[178:181], v[210:213], v[4:7]
	v_mfma_f32_16x16x32_bf16 v[4:7], v[182:185], v[214:217], v[4:7]
	v_mfma_f32_16x16x32_bf16 v[8:11], v[174:177], v[214:217], v[8:11]
	v_mfma_f32_16x16x32_bf16 v[8:11], v[170:173], v[210:213], v[8:11]
	s_setprio 0
	s_barrier
	s_add_i32 vcc_hi, vcc_hi, 2
	s_add_u32 s20, s20, 0x10000
	s_addc_u32 s21, s21, 0
	s_add_u32 s77, s77, 0x10000
	s_addc_u32 vcc_lo, vcc_lo, 0
	s_cmp_gt_u32 vcc_hi, 29
	s_cbranch_scc0 .LBB0_185
	s_and_b64 vcc, exec, s[4:5]
	s_cbranch_vccz .LBB0_188
	s_barrier

; #define PG8_STAGE(bufoff, gbase, voff) do { _Pragma("unroll") for (int _i = 0; _i < 2; ++_i) \
;         __builtin_amdgcn_global_load_lds((const unsigned*)((const char*)(gbase) + (voff)[_i]), (PG8_LAS unsigned*)(lds + (bufoff) + ldsw + _i * 8192), 16, 0, 0); } while (0)
; #define PG8_LDA(dst, b, h) do { _Pragma("unroll") for (int m = 0; m < 4; ++m) _Pragma("unroll") for (int k = 0; k < 2; ++k) dst[m][k] = *(const PG8_LAS bf16x8*)(lds + PG8_SA(b, h) + aoff + m * 2048 + k * 1024); } while (0)
; #define PG8_LDB(dst, b, h) do { _Pragma("unroll") for (int n = 0; n < 2; ++n) _Pragma("unroll") for (int k = 0; k < 2; ++k) dst[n][k] = *(const PG8_LAS bf16x8*)(lds + PG8_SB(b, h) + boff + n * 2048 + k * 1024); } while (0)
; #define PG8_MMA(ai, bj, At, Bt) do { __builtin_amdgcn_s_setprio(1); _Pragma("unroll") for (int m = 0; m < 4; ++m) _Pragma("unroll") for (int n = 0; n < 2; ++n) _Pragma("unroll") for (int k = 0; k < 2; ++k) \
;         acc[ai][bj][m][n] = __builtin_amdgcn_mfma_f32_16x16x32_bf16(Bt[n][k], At[m][k], acc[ai][bj][m][n], 0, 0, 0); __builtin_amdgcn_s_setprio(0); } while (0)
; #define PG8_WAIT_V(n) asm volatile("s_waitcnt vmcnt(" #n ")" ::: "memory")
; template <class Epi, class Sched, bool ALIGN_EPI = false, bool SP2 = false, bool ABLK = false, bool BBLK = false>
; __device__ __forceinline__ void gemm_phase(PG8_LAS unsigned char* lds, const Gemm g, const Sched& S, const Epi& E) {
;     ...
;         for (int t = 0; t < nt; t += 2) {
;             const bool last = (t == nt - 2);
;             const char* a1 = cA + (size_t)(t + 1) * kstepA;
;             const char* a2 = last ? nA : cA + (size_t)(t + 2) * kstepA; const char* b2 = last ? nB : cB + (size_t)(t + 2) * kstepB;
;             const char* a3 = a2 + kstepA; const char* b3 = b2 + kstepB;
;             if (last && has_next) S.a_ready(nxt);
;             if constexpr (SP2) {
;             PG8_LDB(B0, 0, 0); PG8_LDB(B1, 0, 1); PG8_SCHED; PG8_LDA(At, 0, 0); PG8_STAGE(PG8_SA(1, 1), a1 + hstepA, voffA);
;             PG8_WAIT_V(8); PG8_WAIT_L(0); PG8_BAR; PG8_MMA(0, 0, At, B0); PG8_MMA(0, 1, At, B1); PG8_BAR; PG8_SCHED;
;             PG8_LDA(At, 0, 1); PG8_STAGE(PG8_SB(0, 0), b2, voffB); PG8_STAGE(PG8_SB(0, 1), b2 + hstepB, voffB); PG8_STAGE(PG8_SA(0, 0), a2, voffA);
;             PG8_WAIT_V(8); PG8_WAIT_L(0); PG8_BAR; PG8_MMA(1, 0, At, B0); PG8_MMA(1, 1, At, B1); PG8_BAR; PG8_SCHED;
.LBB0_439:
	s_add_u32 s16, s10, 0x4000
	s_addc_u32 s17, s11, 0
	s_cmpk_eq_i32 s13, 0x54
	s_cselect_b32 s20, s0, s16
	s_cselect_b32 s21, s1, s17
	s_cselect_b32 s18, s8, vcc_lo
	s_cselect_b32 s19, s9, vcc_hi
	s_add_u32 s16, s20, 0x8000
	s_addc_u32 s17, s21, 0
	s_add_i32 s68, 0, 0x10000
	v_add_u32_e32 v36, s68, v148
	s_add_i32 s88, 0, 0x14000
	ds_read_b128 v[152:155], v36
	ds_read_b128 v[156:159], v36 offset:1024
	ds_read_b128 v[160:163], v36 offset:2048
	ds_read_b128 v[164:167], v36 offset:3072
	v_add_u32_e32 v36, s88, v148
	ds_read_b128 v[168:171], v36
	ds_read_b128 v[172:175], v36 offset:1024
	ds_read_b128 v[176:179], v36 offset:2048
	ds_read_b128 v[180:183], v36 offset:3072
	s_add_i32 m0, s27, 0xc000
	ds_read_b128 v[184:187], v150
	ds_read_b128 v[188:191], v150 offset:1024
	ds_read_b128 v[192:195], v150 offset:2048
	ds_read_b128 v[196:199], v150 offset:3072
	ds_read_b128 v[200:203], v150 offset:4096
	ds_read_b128 v[204:207], v150 offset:5120
	ds_read_b128 v[208:211], v150 offset:6144
	ds_read_b128 v[212:215], v150 offset:7168
	global_load_lds_dwordx4 v144, s[10:11]
	s_add_i32 m0, s27, 0xe000
	s_nop 0
	global_load_lds_dwordx4 v146, s[10:11]
	s_waitcnt vmcnt(8)
	s_waitcnt lgkmcnt(0)
	v_mfma_f32_16x16x32_bf16 v[132:135], v[152:155], v[184:187], v[132:135]
	v_mfma_f32_16x16x32_bf16 v[132:135], v[156:159], v[188:191], v[132:135]
	v_mfma_f32_16x16x32_bf16 v[128:131], v[164:167], v[188:191], v[128:131]
	v_mfma_f32_16x16x32_bf16 v[128:131], v[160:163], v[184:187], v[128:131]
	s_barrier
	s_setprio 1
	v_mfma_f32_16x16x32_bf16 v[120:123], v[160:163], v[192:195], v[120:123]
	v_mfma_f32_16x16x32_bf16 v[120:123], v[164:167], v[196:199], v[120:123]
	v_mfma_f32_16x16x32_bf16 v[124:127], v[156:159], v[196:199], v[124:127]
	v_mfma_f32_16x16x32_bf16 v[124:127], v[152:155], v[192:195], v[124:127]
	v_mfma_f32_16x16x32_bf16 v[108:111], v[152:155], v[200:203], v[108:111]
	v_mfma_f32_16x16x32_bf16 v[108:111], v[156:159], v[204:207], v[108:111]
	v_mfma_f32_16x16x32_bf16 v[104:107], v[164:167], v[204:207], v[104:107]
	v_mfma_f32_16x16x32_bf16 v[104:107], v[160:163], v[200:203], v[104:107]
	v_mfma_f32_16x16x32_bf16 v[88:91], v[160:163], v[208:211], v[88:91]
	v_mfma_f32_16x16x32_bf16 v[88:91], v[164:167], v[212:215], v[88:91]
	v_mfma_f32_16x16x32_bf16 v[92:95], v[156:159], v[212:215], v[92:95]
	v_mfma_f32_16x16x32_bf16 v[92:95], v[152:155], v[208:211], v[92:95]
	s_setprio 0
	s_setprio 1
	v_mfma_f32_16x16x32_bf16 v[116:119], v[168:171], v[184:187], v[116:119]
	v_mfma_f32_16x16x32_bf16 v[116:119], v[172:175], v[188:191], v[116:119]
	v_mfma_f32_16x16x32_bf16 v[112:115], v[180:183], v[188:191], v[112:115]
	v_mfma_f32_16x16x32_bf16 v[112:115], v[176:179], v[184:187], v[112:115]
	v_mfma_f32_16x16x32_bf16 v[96:99], v[176:179], v[192:195], v[96:99]
	v_mfma_f32_16x16x32_bf16 v[96:99], v[180:183], v[196:199], v[96:99]
	v_mfma_f32_16x16x32_bf16 v[100:103], v[172:175], v[196:199], v[100:103]
	v_mfma_f32_16x16x32_bf16 v[100:103], v[168:171], v[192:195], v[100:103]
	v_mfma_f32_16x16x32_bf16 v[84:87], v[168:171], v[200:203], v[84:87]
	v_mfma_f32_16x16x32_bf16 v[84:87], v[172:175], v[204:207], v[84:87]
	v_mfma_f32_16x16x32_bf16 v[80:83], v[180:183], v[204:207], v[80:83]
	v_mfma_f32_16x16x32_bf16 v[80:83], v[176:179], v[200:203], v[80:83]
	v_mfma_f32_16x16x32_bf16 v[72:75], v[176:179], v[208:211], v[72:75]
	v_mfma_f32_16x16x32_bf16 v[72:75], v[180:183], v[212:215], v[72:75]
	v_mfma_f32_16x16x32_bf16 v[76:79], v[172:175], v[212:215], v[76:79]
	v_mfma_f32_16x16x32_bf16 v[76:79], v[168:171], v[208:211], v[76:79]
	s_setprio 0
	s_barrier
	s_add_i32 s68, s68, s24
	s_mov_b32 m0, s68
	ds_read_b128 v[184:187], v150 offset:16384
	ds_read_b128 v[188:191], v150 offset:17408
	ds_read_b128 v[192:195], v150 offset:18432
	ds_read_b128 v[196:199], v150 offset:19456
	ds_read_b128 v[200:203], v150 offset:20480
	ds_read_b128 v[204:207], v150 offset:21504
	ds_read_b128 v[208:211], v150 offset:22528
	ds_read_b128 v[212:215], v150 offset:23552
	global_load_lds_dwordx4 v138, s[18:19]
	s_add_i32 m0, s68, 0x2000
	s_add_u32 s68, s18, 0x4000
	s_addc_u32 s69, s19, 0
	s_add_i32 s88, s88, s24
	global_load_lds_dwordx4 v142, s[18:19]
	s_mov_b32 m0, s88
	s_nop 0
	global_load_lds_dwordx4 v138, s[68:69]
	s_add_i32 m0, s88, 0x2000
	s_nop 0
	global_load_lds_dwordx4 v142, s[68:69]
	s_mov_b32 m0, s27
	s_nop 0
	global_load_lds_dwordx4 v136, s[20:21]
	s_mov_b32 m0, s28
	s_nop 0
	global_load_lds_dwordx4 v140, s[20:21]
	s_waitcnt vmcnt(8)
	s_waitcnt lgkmcnt(0)
	v_mfma_f32_16x16x32_bf16 v[68:71], v[152:155], v[184:187], v[68:71]
	v_mfma_f32_16x16x32_bf16 v[68:71], v[156:159], v[188:191], v[68:71]
	v_mfma_f32_16x16x32_bf16 v[64:67], v[164:167], v[188:191], v[64:67]
	v_mfma_f32_16x16x32_bf16 v[64:67], v[160:163], v[184:187], v[64:67]
	s_barrier
; #define PG8_STAGE(bufoff, gbase, voff) do { _Pragma("unroll") for (int _i = 0; _i < 2; ++_i) \
;         __builtin_amdgcn_global_load_lds((const unsigned*)((const char*)(gbase) + (voff)[_i]), (PG8_LAS unsigned*)(lds + (bufoff) + ldsw + _i * 8192), 16, 0, 0); } while (0)
; #define PG8_LDA(dst, b, h) do { _Pragma("unroll") for (int m = 0; m < 4; ++m) _Pragma("unroll") for (int k = 0; k < 2; ++k) dst[m][k] = *(const PG8_LAS bf16x8*)(lds + PG8_SA(b, h) + aoff + m * 2048 + k * 1024); } while (0)
; #define PG8_LDB(dst, b, h) do { _Pragma("unroll") for (int n = 0; n < 2; ++n) _Pragma("unroll") for (int k = 0; k < 2; ++k) dst[n][k] = *(const PG8_LAS bf16x8*)(lds + PG8_SB(b, h) + boff + n * 2048 + k * 1024); } while (0)
; #define PG8_MMA(ai, bj, At, Bt) do { __builtin_amdgcn_s_setprio(1); _Pragma("unroll") for (int m = 0; m < 4; ++m) _Pragma("unroll") for (int n = 0; n < 2; ++n) _Pragma("unroll") for (int k = 0; k < 2; ++k) \
;         acc[ai][bj][m][n] = __builtin_amdgcn_mfma_f32_16x16x32_bf16(Bt[n][k], At[m][k], acc[ai][bj][m][n], 0, 0, 0); __builtin_amdgcn_s_setprio(0); } while (0)
; #define PG8_WAIT_V(n) asm volatile("s_waitcnt vmcnt(" #n ")" ::: "memory")
; #define PG8_WAIT_L(n) asm volatile("s_waitcnt lgkmcnt(" #n ")" ::: "memory")
; #define PG8_BAR __builtin_amdgcn_s_barrier()
; #define PG8_SCHED __builtin_amdgcn_sched_barrier(0)
; template <class Epi, class Sched, bool ALIGN_EPI = false, bool SP2 = false, bool ABLK = false, bool BBLK = false>
; __device__ __forceinline__ void gemm_phase(PG8_LAS unsigned char* lds, const Gemm g, const Sched& S, const Epi& E) {
;     ...
;             PG8_WAIT_V(8); PG8_WAIT_L(0); PG8_BAR; PG8_MMA(1, 0, At, B0); PG8_MMA(1, 1, At, B1); PG8_BAR; PG8_SCHED;
;             PG8_LDB(B0, 1, 0); PG8_LDB(B1, 1, 1); PG8_SCHED; PG8_LDA(At, 1, 0); PG8_STAGE(PG8_SA(0, 1), a2 + hstepA, voffA);
;             PG8_WAIT_V(8); PG8_WAIT_L(0); PG8_BAR; PG8_MMA(0, 0, At, B0); PG8_MMA(0, 1, At, B1); PG8_BAR; PG8_SCHED;
;             PG8_LDA(At, 1, 1); PG8_STAGE(PG8_SB(1, 0), b3, voffB); PG8_STAGE(PG8_SB(1, 1), b3 + hstepB, voffB); PG8_STAGE(PG8_SA(1, 0), a3, voffA);
;             PG8_WAIT_V(8); PG8_WAIT_L(0); PG8_BAR; PG8_MMA(1, 0, At, B0); PG8_MMA(1, 1, At, B1); PG8_BAR; PG8_SCHED;
	s_setprio 1
	v_mfma_f32_16x16x32_bf16 v[56:59], v[160:163], v[192:195], v[56:59]
	v_mfma_f32_16x16x32_bf16 v[56:59], v[164:167], v[196:199], v[56:59]
	v_mfma_f32_16x16x32_bf16 v[60:63], v[156:159], v[196:199], v[60:63]
	v_mfma_f32_16x16x32_bf16 v[60:63], v[152:155], v[192:195], v[60:63]
	v_mfma_f32_16x16x32_bf16 v[44:47], v[152:155], v[200:203], v[44:47]
	v_mfma_f32_16x16x32_bf16 v[44:47], v[156:159], v[204:207], v[44:47]
	v_mfma_f32_16x16x32_bf16 v[40:43], v[164:167], v[204:207], v[40:43]
	v_mfma_f32_16x16x32_bf16 v[40:43], v[160:163], v[200:203], v[40:43]
	v_mfma_f32_16x16x32_bf16 v[20:23], v[160:163], v[208:211], v[20:23]
	v_mfma_f32_16x16x32_bf16 v[20:23], v[164:167], v[212:215], v[20:23]
	v_mfma_f32_16x16x32_bf16 v[24:27], v[156:159], v[212:215], v[24:27]
	v_mfma_f32_16x16x32_bf16 v[24:27], v[152:155], v[208:211], v[24:27]
	s_setprio 0
	s_setprio 1
	v_mfma_f32_16x16x32_bf16 v[52:55], v[168:171], v[184:187], v[52:55]
	v_mfma_f32_16x16x32_bf16 v[52:55], v[172:175], v[188:191], v[52:55]
	v_mfma_f32_16x16x32_bf16 v[48:51], v[180:183], v[188:191], v[48:51]
	v_mfma_f32_16x16x32_bf16 v[48:51], v[176:179], v[184:187], v[48:51]
	v_mfma_f32_16x16x32_bf16 v[28:31], v[176:179], v[192:195], v[28:31]
	v_mfma_f32_16x16x32_bf16 v[28:31], v[180:183], v[196:199], v[28:31]
	v_mfma_f32_16x16x32_bf16 v[32:35], v[172:175], v[196:199], v[32:35]
	v_mfma_f32_16x16x32_bf16 v[32:35], v[168:171], v[192:195], v[32:35]
	v_mfma_f32_16x16x32_bf16 v[16:19], v[168:171], v[200:203], v[16:19]
	v_mfma_f32_16x16x32_bf16 v[16:19], v[172:175], v[204:207], v[16:19]
	v_mfma_f32_16x16x32_bf16 v[12:15], v[180:183], v[204:207], v[12:15]
	v_mfma_f32_16x16x32_bf16 v[12:15], v[176:179], v[200:203], v[12:15]
	v_mfma_f32_16x16x32_bf16 v[4:7], v[176:179], v[208:211], v[4:7]
	v_mfma_f32_16x16x32_bf16 v[4:7], v[180:183], v[212:215], v[4:7]
	v_mfma_f32_16x16x32_bf16 v[8:11], v[172:175], v[212:215], v[8:11]
	v_mfma_f32_16x16x32_bf16 v[8:11], v[168:171], v[208:211], v[8:11]
	s_setprio 0
	s_barrier
	s_add_i32 s68, 0, 0x18000
	v_add_u32_e32 v36, s68, v148
	s_add_i32 s69, 0, 0x1c000
	ds_read_b128 v[152:155], v36
	ds_read_b128 v[156:159], v36 offset:1024
	ds_read_b128 v[160:163], v36 offset:2048
	ds_read_b128 v[164:167], v36 offset:3072
	v_add_u32_e32 v36, s69, v148
	ds_read_b128 v[168:171], v36
	ds_read_b128 v[172:175], v36 offset:1024
	ds_read_b128 v[176:179], v36 offset:2048
	ds_read_b128 v[180:183], v36 offset:3072
	s_add_u32 s20, s20, 0x4000
	s_addc_u32 s21, s21, 0
	s_mov_b32 m0, s29
	ds_read_b128 v[184:187], v150 offset:32768
	ds_read_b128 v[188:191], v150 offset:33792
	ds_read_b128 v[192:195], v150 offset:34816
	ds_read_b128 v[196:199], v150 offset:35840
	ds_read_b128 v[200:203], v150 offset:36864
	ds_read_b128 v[204:207], v150 offset:37888
	ds_read_b128 v[208:211], v150 offset:38912
	ds_read_b128 v[212:215], v150 offset:39936
	global_load_lds_dwordx4 v136, s[20:21]
	s_mov_b32 m0, s30
	s_nop 0
	global_load_lds_dwordx4 v140, s[20:21]
	s_waitcnt vmcnt(8)
	s_waitcnt lgkmcnt(0)
	v_mfma_f32_16x16x32_bf16 v[132:135], v[152:155], v[184:187], v[132:135]
	v_mfma_f32_16x16x32_bf16 v[132:135], v[156:159], v[188:191], v[132:135]
	v_mfma_f32_16x16x32_bf16 v[128:131], v[164:167], v[188:191], v[128:131]
	v_mfma_f32_16x16x32_bf16 v[128:131], v[160:163], v[184:187], v[128:131]
	s_barrier
	s_setprio 1
	v_mfma_f32_16x16x32_bf16 v[120:123], v[160:163], v[192:195], v[120:123]
	v_mfma_f32_16x16x32_bf16 v[120:123], v[164:167], v[196:199], v[120:123]
	v_mfma_f32_16x16x32_bf16 v[124:127], v[156:159], v[196:199], v[124:127]
	v_mfma_f32_16x16x32_bf16 v[124:127], v[152:155], v[192:195], v[124:127]
	v_mfma_f32_16x16x32_bf16 v[108:111], v[152:155], v[200:203], v[108:111]
	v_mfma_f32_16x16x32_bf16 v[108:111], v[156:159], v[204:207], v[108:111]
	v_mfma_f32_16x16x32_bf16 v[104:107], v[164:167], v[204:207], v[104:107]
	v_mfma_f32_16x16x32_bf16 v[104:107], v[160:163], v[200:203], v[104:107]
	v_mfma_f32_16x16x32_bf16 v[88:91], v[160:163], v[208:211], v[88:91]
	v_mfma_f32_16x16x32_bf16 v[88:91], v[164:167], v[212:215], v[88:91]
	v_mfma_f32_16x16x32_bf16 v[92:95], v[156:159], v[212:215], v[92:95]
	v_mfma_f32_16x16x32_bf16 v[92:95], v[152:155], v[208:211], v[92:95]
	s_setprio 0
	s_setprio 1
	v_mfma_f32_16x16x32_bf16 v[116:119], v[168:171], v[184:187], v[116:119]
	v_mfma_f32_16x16x32_bf16 v[116:119], v[172:175], v[188:191], v[116:119]
	v_mfma_f32_16x16x32_bf16 v[112:115], v[180:183], v[188:191], v[112:115]
	v_mfma_f32_16x16x32_bf16 v[112:115], v[176:179], v[184:187], v[112:115]
	v_mfma_f32_16x16x32_bf16 v[96:99], v[176:179], v[192:195], v[96:99]
	v_mfma_f32_16x16x32_bf16 v[96:99], v[180:183], v[196:199], v[96:99]
	v_mfma_f32_16x16x32_bf16 v[100:103], v[172:175], v[196:199], v[100:103]
	v_mfma_f32_16x16x32_bf16 v[100:103], v[168:171], v[192:195], v[100:103]
	v_mfma_f32_16x16x32_bf16 v[84:87], v[168:171], v[200:203], v[84:87]
	v_mfma_f32_16x16x32_bf16 v[84:87], v[172:175], v[204:207], v[84:87]
	v_mfma_f32_16x16x32_bf16 v[80:83], v[180:183], v[204:207], v[80:83]
	v_mfma_f32_16x16x32_bf16 v[80:83], v[176:179], v[200:203], v[80:83]
	v_mfma_f32_16x16x32_bf16 v[72:75], v[176:179], v[208:211], v[72:75]
	v_mfma_f32_16x16x32_bf16 v[72:75], v[180:183], v[212:215], v[72:75]
	v_mfma_f32_16x16x32_bf16 v[76:79], v[172:175], v[212:215], v[76:79]
	v_mfma_f32_16x16x32_bf16 v[76:79], v[168:171], v[208:211], v[76:79]
	s_setprio 0
	s_barrier
; #define PG8_STAGE(bufoff, gbase, voff) do { _Pragma("unroll") for (int _i = 0; _i < 2; ++_i) \
;         __builtin_amdgcn_global_load_lds((const unsigned*)((const char*)(gbase) + (voff)[_i]), (PG8_LAS unsigned*)(lds + (bufoff) + ldsw + _i * 8192), 16, 0, 0); } while (0)
; #define PG8_LDA(dst, b, h) do { _Pragma("unroll") for (int m = 0; m < 4; ++m) _Pragma("unroll") for (int k = 0; k < 2; ++k) dst[m][k] = *(const PG8_LAS bf16x8*)(lds + PG8_SA(b, h) + aoff + m * 2048 + k * 1024); } while (0)
; #define PG8_MMA(ai, bj, At, Bt) do { __builtin_amdgcn_s_setprio(1); _Pragma("unroll") for (int m = 0; m < 4; ++m) _Pragma("unroll") for (int n = 0; n < 2; ++n) _Pragma("unroll") for (int k = 0; k < 2; ++k) \
;         acc[ai][bj][m][n] = __builtin_amdgcn_mfma_f32_16x16x32_bf16(Bt[n][k], At[m][k], acc[ai][bj][m][n], 0, 0, 0); __builtin_amdgcn_s_setprio(0); } while (0)
; #define PG8_WAIT_V(n) asm volatile("s_waitcnt vmcnt(" #n ")" ::: "memory")
; #define PG8_WAIT_L(n) asm volatile("s_waitcnt lgkmcnt(" #n ")" ::: "memory")
; #define PG8_BAR __builtin_amdgcn_s_barrier()
; #define PG8_SCHED __builtin_amdgcn_sched_barrier(0)
; template <class Epi, class Sched, bool ALIGN_EPI = false, bool SP2 = false, bool ABLK = false, bool BBLK = false>
; __device__ __forceinline__ void gemm_phase(PG8_LAS unsigned char* lds, const Gemm g, const Sched& S, const Epi& E) {
;     ...
;         for (int t = 0; t < nt; t += 2) {
;             const bool last = (t == nt - 2);
;             const char* a1 = cA + (size_t)(t + 1) * kstepA;
;             const char* a2 = last ? nA : cA + (size_t)(t + 2) * kstepA; const char* b2 = last ? nB : cB + (size_t)(t + 2) * kstepB;
;             const char* a3 = a2 + kstepA; const char* b3 = b2 + kstepB;
;     ...
;             PG8_LDA(At, 1, 1); PG8_STAGE(PG8_SB(1, 0), b3, voffB); PG8_STAGE(PG8_SB(1, 1), b3 + hstepB, voffB); PG8_STAGE(PG8_SA(1, 0), a3, voffA);
;             PG8_WAIT_V(8); PG8_WAIT_L(0); PG8_BAR; PG8_MMA(1, 0, At, B0); PG8_MMA(1, 1, At, B1); PG8_BAR; PG8_SCHED;
	s_add_u32 s20, s18, 0x8000
	s_addc_u32 s21, s19, 0
	s_add_i32 s68, s68, s24
	s_mov_b32 m0, s68
	ds_read_b128 v[184:187], v150 offset:49152
	ds_read_b128 v[188:191], v150 offset:50176
	ds_read_b128 v[192:195], v150 offset:51200
	ds_read_b128 v[196:199], v150 offset:52224
	ds_read_b128 v[200:203], v150 offset:53248
	ds_read_b128 v[204:207], v150 offset:54272
	ds_read_b128 v[208:211], v150 offset:55296
	ds_read_b128 v[212:215], v150 offset:56320
	global_load_lds_dwordx4 v138, s[20:21]
	s_add_i32 m0, s68, 0x2000
	s_add_u32 s18, s18, 0xc000
	s_addc_u32 s19, s19, 0
	global_load_lds_dwordx4 v142, s[20:21]
	s_add_i32 s20, s69, s24
	s_mov_b32 m0, s20
	s_nop 0
	global_load_lds_dwordx4 v138, s[18:19]
	s_add_i32 m0, s20, 0x2000
	s_nop 0
	global_load_lds_dwordx4 v142, s[18:19]
	s_mov_b32 m0, s35
	s_nop 0
	global_load_lds_dwordx4 v136, s[16:17]
	s_mov_b32 m0, s70
	s_nop 0
	global_load_lds_dwordx4 v140, s[16:17]
	s_waitcnt vmcnt(8)
	s_waitcnt lgkmcnt(0)
	v_mfma_f32_16x16x32_bf16 v[68:71], v[152:155], v[184:187], v[68:71]
	v_mfma_f32_16x16x32_bf16 v[68:71], v[156:159], v[188:191], v[68:71]
	v_mfma_f32_16x16x32_bf16 v[64:67], v[164:167], v[188:191], v[64:67]
	v_mfma_f32_16x16x32_bf16 v[64:67], v[160:163], v[184:187], v[64:67]
	s_barrier
	s_setprio 1
	v_mfma_f32_16x16x32_bf16 v[56:59], v[160:163], v[192:195], v[56:59]
	v_mfma_f32_16x16x32_bf16 v[56:59], v[164:167], v[196:199], v[56:59]
	v_mfma_f32_16x16x32_bf16 v[60:63], v[156:159], v[196:199], v[60:63]
	v_mfma_f32_16x16x32_bf16 v[60:63], v[152:155], v[192:195], v[60:63]
	v_mfma_f32_16x16x32_bf16 v[44:47], v[152:155], v[200:203], v[44:47]
	v_mfma_f32_16x16x32_bf16 v[44:47], v[156:159], v[204:207], v[44:47]
	v_mfma_f32_16x16x32_bf16 v[40:43], v[164:167], v[204:207], v[40:43]
	v_mfma_f32_16x16x32_bf16 v[40:43], v[160:163], v[200:203], v[40:43]
	v_mfma_f32_16x16x32_bf16 v[20:23], v[160:163], v[208:211], v[20:23]
	v_mfma_f32_16x16x32_bf16 v[20:23], v[164:167], v[212:215], v[20:23]
	v_mfma_f32_16x16x32_bf16 v[24:27], v[156:159], v[212:215], v[24:27]
	v_mfma_f32_16x16x32_bf16 v[24:27], v[152:155], v[208:211], v[24:27]
	s_setprio 0
	s_setprio 1
	v_mfma_f32_16x16x32_bf16 v[52:55], v[168:171], v[184:187], v[52:55]
	v_mfma_f32_16x16x32_bf16 v[52:55], v[172:175], v[188:191], v[52:55]
	v_mfma_f32_16x16x32_bf16 v[48:51], v[180:183], v[188:191], v[48:51]
	v_mfma_f32_16x16x32_bf16 v[48:51], v[176:179], v[184:187], v[48:51]
	v_mfma_f32_16x16x32_bf16 v[28:31], v[176:179], v[192:195], v[28:31]
	v_mfma_f32_16x16x32_bf16 v[28:31], v[180:183], v[196:199], v[28:31]
	v_mfma_f32_16x16x32_bf16 v[32:35], v[172:175], v[196:199], v[32:35]
	v_mfma_f32_16x16x32_bf16 v[32:35], v[168:171], v[192:195], v[32:35]
	v_mfma_f32_16x16x32_bf16 v[16:19], v[168:171], v[200:203], v[16:19]
	v_mfma_f32_16x16x32_bf16 v[16:19], v[172:175], v[204:207], v[16:19]
	v_mfma_f32_16x16x32_bf16 v[12:15], v[180:183], v[204:207], v[12:15]
	v_mfma_f32_16x16x32_bf16 v[12:15], v[176:179], v[200:203], v[12:15]
	v_mfma_f32_16x16x32_bf16 v[4:7], v[176:179], v[208:211], v[4:7]
	v_mfma_f32_16x16x32_bf16 v[4:7], v[180:183], v[212:215], v[4:7]
	v_mfma_f32_16x16x32_bf16 v[8:11], v[172:175], v[212:215], v[8:11]
	v_mfma_f32_16x16x32_bf16 v[8:11], v[168:171], v[208:211], v[8:11]
	s_setprio 0
	s_barrier
	s_add_i32 s13, s13, 2
	s_add_u32 s10, s10, 0x10000
	s_addc_u32 s11, s11, 0
	s_add_u32 vcc_lo, vcc_lo, 0x10000
	s_addc_u32 vcc_hi, vcc_hi, 0
	s_cmpk_gt_u32 s13, 0x55
	s_cbranch_scc0 .LBB0_439
	s_and_b64 vcc, exec, s[6:7]
	s_cbranch_vccz .LBB0_442
	s_barrier

; #define PG8_STAGE(bufoff, gbase, voff) do { _Pragma("unroll") for (int _i = 0; _i < 2; ++_i) \
;         __builtin_amdgcn_global_load_lds((const unsigned*)((const char*)(gbase) + (voff)[_i]), (PG8_LAS unsigned*)(lds + (bufoff) + ldsw + _i * 8192), 16, 0, 0); } while (0)
; #define PG8_LDA(dst, b, h) do { _Pragma("unroll") for (int m = 0; m < 4; ++m) _Pragma("unroll") for (int k = 0; k < 2; ++k) dst[m][k] = *(const PG8_LAS bf16x8*)(lds + PG8_SA(b, h) + aoff + m * 2048 + k * 1024); } while (0)
; #define PG8_LDB(dst, b, h) do { _Pragma("unroll") for (int n = 0; n < 2; ++n) _Pragma("unroll") for (int k = 0; k < 2; ++k) dst[n][k] = *(const PG8_LAS bf16x8*)(lds + PG8_SB(b, h) + boff + n * 2048 + k * 1024); } while (0)
; #define PG8_MMA(ai, bj, At, Bt) do { __builtin_amdgcn_s_setprio(1); _Pragma("unroll") for (int m = 0; m < 4; ++m) _Pragma("unroll") for (int n = 0; n < 2; ++n) _Pragma("unroll") for (int k = 0; k < 2; ++k) \
;         acc[ai][bj][m][n] = __builtin_amdgcn_mfma_f32_16x16x32_bf16(Bt[n][k], At[m][k], acc[ai][bj][m][n], 0, 0, 0); __builtin_amdgcn_s_setprio(0); } while (0)
; #define PG8_WAIT_V(n) asm volatile("s_waitcnt vmcnt(" #n ")" ::: "memory")
; template <class Epi, class Sched, bool ALIGN_EPI = false, bool SP2 = false, bool ABLK = false, bool BBLK = false>
; __device__ __forceinline__ void gemm_phase(PG8_LAS unsigned char* lds, const Gemm g, const Sched& S, const Epi& E) {
;     ...
;         for (int t = 0; t < nt; t += 2) {
;             const bool last = (t == nt - 2);
;             const char* a1 = cA + (size_t)(t + 1) * kstepA;
;             const char* a2 = last ? nA : cA + (size_t)(t + 2) * kstepA; const char* b2 = last ? nB : cB + (size_t)(t + 2) * kstepB;
;             const char* a3 = a2 + kstepA; const char* b3 = b2 + kstepB;
;             if (last && has_next) S.a_ready(nxt);
;             if constexpr (SP2) {
;             PG8_LDB(B0, 0, 0); PG8_LDB(B1, 0, 1); PG8_SCHED; PG8_LDA(At, 0, 0); PG8_STAGE(PG8_SA(1, 1), a1 + hstepA, voffA);
;             PG8_WAIT_V(8); PG8_WAIT_L(0); PG8_BAR; PG8_MMA(0, 0, At, B0); PG8_MMA(0, 1, At, B1); PG8_BAR; PG8_SCHED;
;             PG8_LDA(At, 0, 1); PG8_STAGE(PG8_SB(0, 0), b2, voffB); PG8_STAGE(PG8_SB(0, 1), b2 + hstepB, voffB); PG8_STAGE(PG8_SA(0, 0), a2, voffA);
;             PG8_WAIT_V(8); PG8_WAIT_L(0); PG8_BAR; PG8_MMA(1, 0, At, B0); PG8_MMA(1, 1, At, B1); PG8_BAR; PG8_SCHED;
.LBB0_916:
	s_add_u32 s22, s20, 0x4000
	s_addc_u32 s23, s21, 0
	s_cmp_eq_u32 s13, 28
	s_cselect_b32 s26, s19, s22
	s_cselect_b32 s27, s1, s23
	s_cselect_b32 s24, s65, s70
	s_cselect_b32 s25, s9, s71
	s_add_u32 s22, s26, 0x8000
	s_addc_u32 s23, s27, 0
	s_add_i32 s68, 0, 0x10000
	v_add_u32_e32 v36, s68, v155
	s_add_i32 s77, 0, 0x14000
	ds_read_b128 v[150:153], v36
	ds_read_b128 v[158:161], v36 offset:1024
	ds_read_b128 v[162:165], v36 offset:2048
	ds_read_b128 v[166:169], v36 offset:3072
	v_add_u32_e32 v36, s77, v155
	ds_read_b128 v[170:173], v36
	ds_read_b128 v[174:177], v36 offset:1024
	ds_read_b128 v[178:181], v36 offset:2048
	ds_read_b128 v[182:185], v36 offset:3072
	s_add_i32 m0, s31, 0xc000
	ds_read_b128 v[186:189], v157
	ds_read_b128 v[190:193], v157 offset:1024
	ds_read_b128 v[194:197], v157 offset:2048
	ds_read_b128 v[198:201], v157 offset:3072
	ds_read_b128 v[202:205], v157 offset:4096
	ds_read_b128 v[206:209], v157 offset:5120
	ds_read_b128 v[210:213], v157 offset:6144
	ds_read_b128 v[214:217], v157 offset:7168
	global_load_lds_dwordx4 v146, s[20:21]
	s_add_i32 m0, s31, 0xe000
	s_nop 0
	global_load_lds_dwordx4 v148, s[20:21]
	s_waitcnt vmcnt(8)
	s_waitcnt lgkmcnt(0)
	v_mfma_f32_16x16x32_bf16 v[132:135], v[150:153], v[186:189], v[132:135]
	v_mfma_f32_16x16x32_bf16 v[132:135], v[158:161], v[190:193], v[132:135]
	v_mfma_f32_16x16x32_bf16 v[128:131], v[166:169], v[190:193], v[128:131]
	v_mfma_f32_16x16x32_bf16 v[128:131], v[162:165], v[186:189], v[128:131]
	s_barrier
	s_setprio 1
	v_mfma_f32_16x16x32_bf16 v[116:119], v[162:165], v[194:197], v[116:119]
	v_mfma_f32_16x16x32_bf16 v[116:119], v[166:169], v[198:201], v[116:119]
	v_mfma_f32_16x16x32_bf16 v[124:127], v[158:161], v[198:201], v[124:127]
	v_mfma_f32_16x16x32_bf16 v[124:127], v[150:153], v[194:197], v[124:127]
	v_mfma_f32_16x16x32_bf16 v[108:111], v[150:153], v[202:205], v[108:111]
	v_mfma_f32_16x16x32_bf16 v[108:111], v[158:161], v[206:209], v[108:111]
	v_mfma_f32_16x16x32_bf16 v[100:103], v[166:169], v[206:209], v[100:103]
	v_mfma_f32_16x16x32_bf16 v[100:103], v[162:165], v[202:205], v[100:103]
	v_mfma_f32_16x16x32_bf16 v[84:87], v[162:165], v[210:213], v[84:87]
	v_mfma_f32_16x16x32_bf16 v[84:87], v[166:169], v[214:217], v[84:87]
	v_mfma_f32_16x16x32_bf16 v[92:95], v[158:161], v[214:217], v[92:95]
	v_mfma_f32_16x16x32_bf16 v[92:95], v[150:153], v[210:213], v[92:95]
	s_setprio 0
	s_setprio 1
	v_mfma_f32_16x16x32_bf16 v[120:123], v[170:173], v[186:189], v[120:123]
	v_mfma_f32_16x16x32_bf16 v[120:123], v[174:177], v[190:193], v[120:123]
	v_mfma_f32_16x16x32_bf16 v[112:115], v[182:185], v[190:193], v[112:115]
	v_mfma_f32_16x16x32_bf16 v[112:115], v[178:181], v[186:189], v[112:115]
	v_mfma_f32_16x16x32_bf16 v[96:99], v[178:181], v[194:197], v[96:99]
	v_mfma_f32_16x16x32_bf16 v[96:99], v[182:185], v[198:201], v[96:99]
	v_mfma_f32_16x16x32_bf16 v[104:107], v[174:177], v[198:201], v[104:107]
	v_mfma_f32_16x16x32_bf16 v[104:107], v[170:173], v[194:197], v[104:107]
	v_mfma_f32_16x16x32_bf16 v[88:91], v[170:173], v[202:205], v[88:91]
	v_mfma_f32_16x16x32_bf16 v[88:91], v[174:177], v[206:209], v[88:91]
	v_mfma_f32_16x16x32_bf16 v[80:83], v[182:185], v[206:209], v[80:83]
	v_mfma_f32_16x16x32_bf16 v[80:83], v[178:181], v[202:205], v[80:83]
	v_mfma_f32_16x16x32_bf16 v[72:75], v[178:181], v[210:213], v[72:75]
	v_mfma_f32_16x16x32_bf16 v[72:75], v[182:185], v[214:217], v[72:75]
	v_mfma_f32_16x16x32_bf16 v[76:79], v[174:177], v[214:217], v[76:79]
	v_mfma_f32_16x16x32_bf16 v[76:79], v[170:173], v[210:213], v[76:79]
	s_setprio 0
	s_barrier
	s_add_i32 s68, s68, s29
	s_mov_b32 m0, s68
	ds_read_b128 v[186:189], v157 offset:16384
	ds_read_b128 v[190:193], v157 offset:17408
	ds_read_b128 v[194:197], v157 offset:18432
	ds_read_b128 v[198:201], v157 offset:19456
	ds_read_b128 v[202:205], v157 offset:20480
	ds_read_b128 v[206:209], v157 offset:21504
	ds_read_b128 v[210:213], v157 offset:22528
	ds_read_b128 v[214:217], v157 offset:23552
	global_load_lds_dwordx4 v140, s[24:25]
	s_add_i32 m0, s68, 0x2000
	s_add_u32 s68, s24, 0x4000
	s_addc_u32 s69, s25, 0
	s_add_i32 s77, s77, s29
	global_load_lds_dwordx4 v136, s[24:25]
	s_mov_b32 m0, s77
	s_nop 0
	global_load_lds_dwordx4 v140, s[68:69]
	s_add_i32 m0, s77, 0x2000
	s_nop 0
	global_load_lds_dwordx4 v136, s[68:69]
	s_mov_b32 m0, s31
	s_nop 0
	global_load_lds_dwordx4 v142, s[26:27]
	s_mov_b32 m0, s34
	s_nop 0
	global_load_lds_dwordx4 v138, s[26:27]
	s_waitcnt vmcnt(8)
	s_waitcnt lgkmcnt(0)
	v_mfma_f32_16x16x32_bf16 v[68:71], v[150:153], v[186:189], v[68:71]
	v_mfma_f32_16x16x32_bf16 v[68:71], v[158:161], v[190:193], v[68:71]
	v_mfma_f32_16x16x32_bf16 v[64:67], v[166:169], v[190:193], v[64:67]
	v_mfma_f32_16x16x32_bf16 v[64:67], v[162:165], v[186:189], v[64:67]
	s_barrier
; #define PG8_STAGE(bufoff, gbase, voff) do { _Pragma("unroll") for (int _i = 0; _i < 2; ++_i) \
;         __builtin_amdgcn_global_load_lds((const unsigned*)((const char*)(gbase) + (voff)[_i]), (PG8_LAS unsigned*)(lds + (bufoff) + ldsw + _i * 8192), 16, 0, 0); } while (0)
; #define PG8_LDA(dst, b, h) do { _Pragma("unroll") for (int m = 0; m < 4; ++m) _Pragma("unroll") for (int k = 0; k < 2; ++k) dst[m][k] = *(const PG8_LAS bf16x8*)(lds + PG8_SA(b, h) + aoff + m * 2048 + k * 1024); } while (0)
; #define PG8_LDB(dst, b, h) do { _Pragma("unroll") for (int n = 0; n < 2; ++n) _Pragma("unroll") for (int k = 0; k < 2; ++k) dst[n][k] = *(const PG8_LAS bf16x8*)(lds + PG8_SB(b, h) + boff + n * 2048 + k * 1024); } while (0)
; #define PG8_MMA(ai, bj, At, Bt) do { __builtin_amdgcn_s_setprio(1); _Pragma("unroll") for (int m = 0; m < 4; ++m) _Pragma("unroll") for (int n = 0; n < 2; ++n) _Pragma("unroll") for (int k = 0; k < 2; ++k) \
;         acc[ai][bj][m][n] = __builtin_amdgcn_mfma_f32_16x16x32_bf16(Bt[n][k], At[m][k], acc[ai][bj][m][n], 0, 0, 0); __builtin_amdgcn_s_setprio(0); } while (0)
; #define PG8_WAIT_V(n) asm volatile("s_waitcnt vmcnt(" #n ")" ::: "memory")
; #define PG8_WAIT_L(n) asm volatile("s_waitcnt lgkmcnt(" #n ")" ::: "memory")
; #define PG8_BAR __builtin_amdgcn_s_barrier()
; #define PG8_SCHED __builtin_amdgcn_sched_barrier(0)
; template <class Epi, class Sched, bool ALIGN_EPI = false, bool SP2 = false, bool ABLK = false, bool BBLK = false>
; __device__ __forceinline__ void gemm_phase(PG8_LAS unsigned char* lds, const Gemm g, const Sched& S, const Epi& E) {
;     ...
;             PG8_WAIT_V(8); PG8_WAIT_L(0); PG8_BAR; PG8_MMA(1, 0, At, B0); PG8_MMA(1, 1, At, B1); PG8_BAR; PG8_SCHED;
;             PG8_LDB(B0, 1, 0); PG8_LDB(B1, 1, 1); PG8_SCHED; PG8_LDA(At, 1, 0); PG8_STAGE(PG8_SA(0, 1), a2 + hstepA, voffA);
;             PG8_WAIT_V(8); PG8_WAIT_L(0); PG8_BAR; PG8_MMA(0, 0, At, B0); PG8_MMA(0, 1, At, B1); PG8_BAR; PG8_SCHED;
;             PG8_LDA(At, 1, 1); PG8_STAGE(PG8_SB(1, 0), b3, voffB); PG8_STAGE(PG8_SB(1, 1), b3 + hstepB, voffB); PG8_STAGE(PG8_SA(1, 0), a3, voffA);
;             PG8_WAIT_V(8); PG8_WAIT_L(0); PG8_BAR; PG8_MMA(1, 0, At, B0); PG8_MMA(1, 1, At, B1); PG8_BAR; PG8_SCHED;
	s_setprio 1
	v_mfma_f32_16x16x32_bf16 v[52:55], v[162:165], v[194:197], v[52:55]
	v_mfma_f32_16x16x32_bf16 v[52:55], v[166:169], v[198:201], v[52:55]
	v_mfma_f32_16x16x32_bf16 v[60:63], v[158:161], v[198:201], v[60:63]
	v_mfma_f32_16x16x32_bf16 v[60:63], v[150:153], v[194:197], v[60:63]
	v_mfma_f32_16x16x32_bf16 v[44:47], v[150:153], v[202:205], v[44:47]
	v_mfma_f32_16x16x32_bf16 v[44:47], v[158:161], v[206:209], v[44:47]
	v_mfma_f32_16x16x32_bf16 v[32:35], v[166:169], v[206:209], v[32:35]
	v_mfma_f32_16x16x32_bf16 v[32:35], v[162:165], v[202:205], v[32:35]
	v_mfma_f32_16x16x32_bf16 v[16:19], v[162:165], v[210:213], v[16:19]
	v_mfma_f32_16x16x32_bf16 v[16:19], v[166:169], v[214:217], v[16:19]
	v_mfma_f32_16x16x32_bf16 v[24:27], v[158:161], v[214:217], v[24:27]
	v_mfma_f32_16x16x32_bf16 v[24:27], v[150:153], v[210:213], v[24:27]
	s_setprio 0
	s_setprio 1
	v_mfma_f32_16x16x32_bf16 v[56:59], v[170:173], v[186:189], v[56:59]
	v_mfma_f32_16x16x32_bf16 v[56:59], v[174:177], v[190:193], v[56:59]
	v_mfma_f32_16x16x32_bf16 v[48:51], v[182:185], v[190:193], v[48:51]
	v_mfma_f32_16x16x32_bf16 v[48:51], v[178:181], v[186:189], v[48:51]
	v_mfma_f32_16x16x32_bf16 v[28:31], v[178:181], v[194:197], v[28:31]
	v_mfma_f32_16x16x32_bf16 v[28:31], v[182:185], v[198:201], v[28:31]
	v_mfma_f32_16x16x32_bf16 v[40:43], v[174:177], v[198:201], v[40:43]
	v_mfma_f32_16x16x32_bf16 v[40:43], v[170:173], v[194:197], v[40:43]
	v_mfma_f32_16x16x32_bf16 v[20:23], v[170:173], v[202:205], v[20:23]
	v_mfma_f32_16x16x32_bf16 v[20:23], v[174:177], v[206:209], v[20:23]
	v_mfma_f32_16x16x32_bf16 v[12:15], v[182:185], v[206:209], v[12:15]
	v_mfma_f32_16x16x32_bf16 v[12:15], v[178:181], v[202:205], v[12:15]
	v_mfma_f32_16x16x32_bf16 v[4:7], v[178:181], v[210:213], v[4:7]
	v_mfma_f32_16x16x32_bf16 v[4:7], v[182:185], v[214:217], v[4:7]
	v_mfma_f32_16x16x32_bf16 v[8:11], v[174:177], v[214:217], v[8:11]
	v_mfma_f32_16x16x32_bf16 v[8:11], v[170:173], v[210:213], v[8:11]
	s_setprio 0
	s_barrier
	s_add_i32 s68, 0, 0x18000
	v_add_u32_e32 v36, s68, v155
	s_add_i32 s69, 0, 0x1c000
	ds_read_b128 v[150:153], v36
	ds_read_b128 v[158:161], v36 offset:1024
	ds_read_b128 v[162:165], v36 offset:2048
	ds_read_b128 v[166:169], v36 offset:3072
	v_add_u32_e32 v36, s69, v155
	ds_read_b128 v[170:173], v36
	ds_read_b128 v[174:177], v36 offset:1024
	ds_read_b128 v[178:181], v36 offset:2048
	ds_read_b128 v[182:185], v36 offset:3072
	s_add_u32 s26, s26, 0x4000
	s_addc_u32 s27, s27, 0
	s_mov_b32 m0, s35
	ds_read_b128 v[186:189], v157 offset:32768
	ds_read_b128 v[190:193], v157 offset:33792
	ds_read_b128 v[194:197], v157 offset:34816
	ds_read_b128 v[198:201], v157 offset:35840
	ds_read_b128 v[202:205], v157 offset:36864
	ds_read_b128 v[206:209], v157 offset:37888
	ds_read_b128 v[210:213], v157 offset:38912
	ds_read_b128 v[214:217], v157 offset:39936
	global_load_lds_dwordx4 v142, s[26:27]
	s_mov_b32 m0, s36
	s_nop 0
	global_load_lds_dwordx4 v138, s[26:27]
	s_waitcnt vmcnt(8)
	s_waitcnt lgkmcnt(0)
	v_mfma_f32_16x16x32_bf16 v[132:135], v[150:153], v[186:189], v[132:135]
	v_mfma_f32_16x16x32_bf16 v[132:135], v[158:161], v[190:193], v[132:135]
	v_mfma_f32_16x16x32_bf16 v[128:131], v[166:169], v[190:193], v[128:131]
	v_mfma_f32_16x16x32_bf16 v[128:131], v[162:165], v[186:189], v[128:131]
	s_barrier
	s_setprio 1
	v_mfma_f32_16x16x32_bf16 v[116:119], v[162:165], v[194:197], v[116:119]
	v_mfma_f32_16x16x32_bf16 v[116:119], v[166:169], v[198:201], v[116:119]
	v_mfma_f32_16x16x32_bf16 v[124:127], v[158:161], v[198:201], v[124:127]
	v_mfma_f32_16x16x32_bf16 v[124:127], v[150:153], v[194:197], v[124:127]
	v_mfma_f32_16x16x32_bf16 v[108:111], v[150:153], v[202:205], v[108:111]
	v_mfma_f32_16x16x32_bf16 v[108:111], v[158:161], v[206:209], v[108:111]
	v_mfma_f32_16x16x32_bf16 v[100:103], v[166:169], v[206:209], v[100:103]
	v_mfma_f32_16x16x32_bf16 v[100:103], v[162:165], v[202:205], v[100:103]
	v_mfma_f32_16x16x32_bf16 v[84:87], v[162:165], v[210:213], v[84:87]
	v_mfma_f32_16x16x32_bf16 v[84:87], v[166:169], v[214:217], v[84:87]
	v_mfma_f32_16x16x32_bf16 v[92:95], v[158:161], v[214:217], v[92:95]
	v_mfma_f32_16x16x32_bf16 v[92:95], v[150:153], v[210:213], v[92:95]
	s_setprio 0
	s_setprio 1
	v_mfma_f32_16x16x32_bf16 v[120:123], v[170:173], v[186:189], v[120:123]
	v_mfma_f32_16x16x32_bf16 v[120:123], v[174:177], v[190:193], v[120:123]
	v_mfma_f32_16x16x32_bf16 v[112:115], v[182:185], v[190:193], v[112:115]
	v_mfma_f32_16x16x32_bf16 v[112:115], v[178:181], v[186:189], v[112:115]
	v_mfma_f32_16x16x32_bf16 v[96:99], v[178:181], v[194:197], v[96:99]
	v_mfma_f32_16x16x32_bf16 v[96:99], v[182:185], v[198:201], v[96:99]
	v_mfma_f32_16x16x32_bf16 v[104:107], v[174:177], v[198:201], v[104:107]
	v_mfma_f32_16x16x32_bf16 v[104:107], v[170:173], v[194:197], v[104:107]
	v_mfma_f32_16x16x32_bf16 v[88:91], v[170:173], v[202:205], v[88:91]
	v_mfma_f32_16x16x32_bf16 v[88:91], v[174:177], v[206:209], v[88:91]
	v_mfma_f32_16x16x32_bf16 v[80:83], v[182:185], v[206:209], v[80:83]
	v_mfma_f32_16x16x32_bf16 v[80:83], v[178:181], v[202:205], v[80:83]
	v_mfma_f32_16x16x32_bf16 v[72:75], v[178:181], v[210:213], v[72:75]
	v_mfma_f32_16x16x32_bf16 v[72:75], v[182:185], v[214:217], v[72:75]
	v_mfma_f32_16x16x32_bf16 v[76:79], v[174:177], v[214:217], v[76:79]
	v_mfma_f32_16x16x32_bf16 v[76:79], v[170:173], v[210:213], v[76:79]
	s_setprio 0
	s_barrier
; #define PG8_STAGE(bufoff, gbase, voff) do { _Pragma("unroll") for (int _i = 0; _i < 2; ++_i) \
;         __builtin_amdgcn_global_load_lds((const unsigned*)((const char*)(gbase) + (voff)[_i]), (PG8_LAS unsigned*)(lds + (bufoff) + ldsw + _i * 8192), 16, 0, 0); } while (0)
; #define PG8_LDA(dst, b, h) do { _Pragma("unroll") for (int m = 0; m < 4; ++m) _Pragma("unroll") for (int k = 0; k < 2; ++k) dst[m][k] = *(const PG8_LAS bf16x8*)(lds + PG8_SA(b, h) + aoff + m * 2048 + k * 1024); } while (0)
; #define PG8_MMA(ai, bj, At, Bt) do { __builtin_amdgcn_s_setprio(1); _Pragma("unroll") for (int m = 0; m < 4; ++m) _Pragma("unroll") for (int n = 0; n < 2; ++n) _Pragma("unroll") for (int k = 0; k < 2; ++k) \
;         acc[ai][bj][m][n] = __builtin_amdgcn_mfma_f32_16x16x32_bf16(Bt[n][k], At[m][k], acc[ai][bj][m][n], 0, 0, 0); __builtin_amdgcn_s_setprio(0); } while (0)
; #define PG8_WAIT_V(n) asm volatile("s_waitcnt vmcnt(" #n ")" ::: "memory")
; #define PG8_WAIT_L(n) asm volatile("s_waitcnt lgkmcnt(" #n ")" ::: "memory")
; #define PG8_BAR __builtin_amdgcn_s_barrier()
; #define PG8_SCHED __builtin_amdgcn_sched_barrier(0)
; template <class Epi, class Sched, bool ALIGN_EPI = false, bool SP2 = false, bool ABLK = false, bool BBLK = false>
; __device__ __forceinline__ void gemm_phase(PG8_LAS unsigned char* lds, const Gemm g, const Sched& S, const Epi& E) {
;     ...
;         for (int t = 0; t < nt; t += 2) {
;             const bool last = (t == nt - 2);
;             const char* a1 = cA + (size_t)(t + 1) * kstepA;
;             const char* a2 = last ? nA : cA + (size_t)(t + 2) * kstepA; const char* b2 = last ? nB : cB + (size_t)(t + 2) * kstepB;
;             const char* a3 = a2 + kstepA; const char* b3 = b2 + kstepB;
;     ...
;             PG8_LDA(At, 1, 1); PG8_STAGE(PG8_SB(1, 0), b3, voffB); PG8_STAGE(PG8_SB(1, 1), b3 + hstepB, voffB); PG8_STAGE(PG8_SA(1, 0), a3, voffA);
;             PG8_WAIT_V(8); PG8_WAIT_L(0); PG8_BAR; PG8_MMA(1, 0, At, B0); PG8_MMA(1, 1, At, B1); PG8_BAR; PG8_SCHED;
	s_add_u32 s26, s24, 0x8000
	s_addc_u32 s27, s25, 0
	s_add_i32 s68, s68, s29
	s_mov_b32 m0, s68
	ds_read_b128 v[186:189], v157 offset:49152
	ds_read_b128 v[190:193], v157 offset:50176
	ds_read_b128 v[194:197], v157 offset:51200
	ds_read_b128 v[198:201], v157 offset:52224
	ds_read_b128 v[202:205], v157 offset:53248
	ds_read_b128 v[206:209], v157 offset:54272
	ds_read_b128 v[210:213], v157 offset:55296
	ds_read_b128 v[214:217], v157 offset:56320
	global_load_lds_dwordx4 v140, s[26:27]
	s_add_i32 m0, s68, 0x2000
	s_add_u32 s24, s24, 0xc000
	s_addc_u32 s25, s25, 0
	global_load_lds_dwordx4 v136, s[26:27]
	s_add_i32 s26, s69, s29
	s_mov_b32 m0, s26
	s_nop 0
	global_load_lds_dwordx4 v140, s[24:25]
	s_add_i32 m0, s26, 0x2000
	s_nop 0
	global_load_lds_dwordx4 v136, s[24:25]
	s_mov_b32 m0, s37
	s_nop 0
	global_load_lds_dwordx4 v142, s[22:23]
	s_mov_b32 m0, s62
	s_nop 0
	global_load_lds_dwordx4 v138, s[22:23]
	s_waitcnt vmcnt(8)
	s_waitcnt lgkmcnt(0)
	v_mfma_f32_16x16x32_bf16 v[68:71], v[150:153], v[186:189], v[68:71]
	v_mfma_f32_16x16x32_bf16 v[68:71], v[158:161], v[190:193], v[68:71]
	v_mfma_f32_16x16x32_bf16 v[64:67], v[166:169], v[190:193], v[64:67]
	v_mfma_f32_16x16x32_bf16 v[64:67], v[162:165], v[186:189], v[64:67]
	s_barrier
	s_setprio 1
	v_mfma_f32_16x16x32_bf16 v[52:55], v[162:165], v[194:197], v[52:55]
	v_mfma_f32_16x16x32_bf16 v[52:55], v[166:169], v[198:201], v[52:55]
	v_mfma_f32_16x16x32_bf16 v[60:63], v[158:161], v[198:201], v[60:63]
	v_mfma_f32_16x16x32_bf16 v[60:63], v[150:153], v[194:197], v[60:63]
	v_mfma_f32_16x16x32_bf16 v[44:47], v[150:153], v[202:205], v[44:47]
	v_mfma_f32_16x16x32_bf16 v[44:47], v[158:161], v[206:209], v[44:47]
	v_mfma_f32_16x16x32_bf16 v[32:35], v[166:169], v[206:209], v[32:35]
	v_mfma_f32_16x16x32_bf16 v[32:35], v[162:165], v[202:205], v[32:35]
	v_mfma_f32_16x16x32_bf16 v[16:19], v[162:165], v[210:213], v[16:19]
	v_mfma_f32_16x16x32_bf16 v[16:19], v[166:169], v[214:217], v[16:19]
	v_mfma_f32_16x16x32_bf16 v[24:27], v[158:161], v[214:217], v[24:27]
	v_mfma_f32_16x16x32_bf16 v[24:27], v[150:153], v[210:213], v[24:27]
	s_setprio 0
	s_setprio 1
	v_mfma_f32_16x16x32_bf16 v[56:59], v[170:173], v[186:189], v[56:59]
	v_mfma_f32_16x16x32_bf16 v[56:59], v[174:177], v[190:193], v[56:59]
	v_mfma_f32_16x16x32_bf16 v[48:51], v[182:185], v[190:193], v[48:51]
	v_mfma_f32_16x16x32_bf16 v[48:51], v[178:181], v[186:189], v[48:51]
	v_mfma_f32_16x16x32_bf16 v[28:31], v[178:181], v[194:197], v[28:31]
	v_mfma_f32_16x16x32_bf16 v[28:31], v[182:185], v[198:201], v[28:31]
	v_mfma_f32_16x16x32_bf16 v[40:43], v[174:177], v[198:201], v[40:43]
	v_mfma_f32_16x16x32_bf16 v[40:43], v[170:173], v[194:197], v[40:43]
	v_mfma_f32_16x16x32_bf16 v[20:23], v[170:173], v[202:205], v[20:23]
	v_mfma_f32_16x16x32_bf16 v[20:23], v[174:177], v[206:209], v[20:23]
	v_mfma_f32_16x16x32_bf16 v[12:15], v[182:185], v[206:209], v[12:15]
	v_mfma_f32_16x16x32_bf16 v[12:15], v[178:181], v[202:205], v[12:15]
	v_mfma_f32_16x16x32_bf16 v[4:7], v[178:181], v[210:213], v[4:7]
	v_mfma_f32_16x16x32_bf16 v[4:7], v[182:185], v[214:217], v[4:7]
	v_mfma_f32_16x16x32_bf16 v[8:11], v[174:177], v[214:217], v[8:11]
	v_mfma_f32_16x16x32_bf16 v[8:11], v[170:173], v[210:213], v[8:11]
	s_setprio 0
	s_barrier
	s_add_i32 s13, s13, 2
	s_add_u32 s20, s20, 0x10000
	s_addc_u32 s21, s21, 0
	s_add_u32 s70, s70, 0x10000
	s_addc_u32 s71, s71, 0
	s_cmp_gt_u32 s13, 29
	s_cbranch_scc0 .LBB0_916
	s_and_b64 vcc, exec, s[6:7]
	s_cbranch_vccz .LBB0_919
	s_barrier

; #define PG8_STAGE(bufoff, gbase, voff) do { _Pragma("unroll") for (int _i = 0; _i < 2; ++_i) \
;         __builtin_amdgcn_global_load_lds((const unsigned*)((const char*)(gbase) + (voff)[_i]), (PG8_LAS unsigned*)(lds + (bufoff) + ldsw + _i * 8192), 16, 0, 0); } while (0)
; #define PG8_LDA(dst, b, h) do { _Pragma("unroll") for (int m = 0; m < 4; ++m) _Pragma("unroll") for (int k = 0; k < 2; ++k) dst[m][k] = *(const PG8_LAS bf16x8*)(lds + PG8_SA(b, h) + aoff + m * 2048 + k * 1024); } while (0)
; #define PG8_LDB(dst, b, h) do { _Pragma("unroll") for (int n = 0; n < 2; ++n) _Pragma("unroll") for (int k = 0; k < 2; ++k) dst[n][k] = *(const PG8_LAS bf16x8*)(lds + PG8_SB(b, h) + boff + n * 2048 + k * 1024); } while (0)
; #define PG8_MMA(ai, bj, At, Bt) do { __builtin_amdgcn_s_setprio(1); _Pragma("unroll") for (int m = 0; m < 4; ++m) _Pragma("unroll") for (int n = 0; n < 2; ++n) _Pragma("unroll") for (int k = 0; k < 2; ++k) \
;         acc[ai][bj][m][n] = __builtin_amdgcn_mfma_f32_16x16x32_bf16(Bt[n][k], At[m][k], acc[ai][bj][m][n], 0, 0, 0); __builtin_amdgcn_s_setprio(0); } while (0)
; #define PG8_WAIT_V(n) asm volatile("s_waitcnt vmcnt(" #n ")" ::: "memory")
; template <class Epi, class Sched, bool ALIGN_EPI = false, bool SP2 = false, bool ABLK = false, bool BBLK = false>
; __device__ __forceinline__ void gemm_phase(PG8_LAS unsigned char* lds, const Gemm g, const Sched& S, const Epi& E) {
;     ...
;         for (int t = 0; t < nt; t += 2) {
;             const bool last = (t == nt - 2);
;             const char* a1 = cA + (size_t)(t + 1) * kstepA;
;             const char* a2 = last ? nA : cA + (size_t)(t + 2) * kstepA; const char* b2 = last ? nB : cB + (size_t)(t + 2) * kstepB;
;             const char* a3 = a2 + kstepA; const char* b3 = b2 + kstepB;
;             if (last && has_next) S.a_ready(nxt);
;             if constexpr (SP2) {
;             PG8_LDB(B0, 0, 0); PG8_LDB(B1, 0, 1); PG8_SCHED; PG8_LDA(At, 0, 0); PG8_STAGE(PG8_SA(1, 1), a1 + hstepA, voffA);
;             PG8_WAIT_V(8); PG8_WAIT_L(0); PG8_BAR; PG8_MMA(0, 0, At, B0); PG8_MMA(0, 1, At, B1); PG8_BAR; PG8_SCHED;
;             PG8_LDA(At, 0, 1); PG8_STAGE(PG8_SB(0, 0), b2, voffB); PG8_STAGE(PG8_SB(0, 1), b2 + hstepB, voffB); PG8_STAGE(PG8_SA(0, 0), a2, voffA);
;             PG8_WAIT_V(8); PG8_WAIT_L(0); PG8_BAR; PG8_MMA(1, 0, At, B0); PG8_MMA(1, 1, At, B1); PG8_BAR; PG8_SCHED;
.LBB0_2111:
	s_add_u32 s24, s22, 0x4000
	s_addc_u32 s25, s23, 0
	s_cmp_eq_u32 s13, 28
	s_cselect_b32 s28, s17, s24
	s_cselect_b32 s29, s12, s25
	s_cselect_b32 s26, s77, s82
	s_cselect_b32 s27, s11, vcc_lo
	s_add_u32 s24, s28, 0x8000
	s_addc_u32 s25, s29, 0
	s_add_i32 s68, 0, 0x10000
	v_add_u32_e32 v151, s68, v148
	s_add_i32 s88, 0, 0x14000
	ds_read_b128 v[36:39], v151
	ds_read_b128 v[152:155], v151 offset:1024
	ds_read_b128 v[156:159], v151 offset:2048
	ds_read_b128 v[160:163], v151 offset:3072
	v_add_u32_e32 v151, s88, v148
	ds_read_b128 v[164:167], v151
	ds_read_b128 v[168:171], v151 offset:1024
	ds_read_b128 v[172:175], v151 offset:2048
	ds_read_b128 v[176:179], v151 offset:3072
	s_add_i32 m0, s9, 0xc000
	ds_read_b128 v[180:183], v150
	ds_read_b128 v[184:187], v150 offset:1024
	ds_read_b128 v[188:191], v150 offset:2048
	ds_read_b128 v[192:195], v150 offset:3072
	ds_read_b128 v[196:199], v150 offset:4096
	ds_read_b128 v[200:203], v150 offset:5120
	ds_read_b128 v[204:207], v150 offset:6144
	ds_read_b128 v[208:211], v150 offset:7168
	global_load_lds_dwordx4 v144, s[22:23]
	s_add_i32 m0, s9, 0xe000
	s_nop 0
	global_load_lds_dwordx4 v146, s[22:23]
	s_waitcnt vmcnt(8)
	s_waitcnt lgkmcnt(0)
	v_mfma_f32_16x16x32_bf16 v[132:135], v[36:39], v[180:183], v[132:135]
	v_mfma_f32_16x16x32_bf16 v[132:135], v[152:155], v[184:187], v[132:135]
	v_mfma_f32_16x16x32_bf16 v[128:131], v[160:163], v[184:187], v[128:131]
	v_mfma_f32_16x16x32_bf16 v[128:131], v[156:159], v[180:183], v[128:131]
	s_barrier
	s_setprio 1
	v_mfma_f32_16x16x32_bf16 v[120:123], v[156:159], v[188:191], v[120:123]
	v_mfma_f32_16x16x32_bf16 v[120:123], v[160:163], v[192:195], v[120:123]
	v_mfma_f32_16x16x32_bf16 v[124:127], v[152:155], v[192:195], v[124:127]
	v_mfma_f32_16x16x32_bf16 v[124:127], v[36:39], v[188:191], v[124:127]
	v_mfma_f32_16x16x32_bf16 v[108:111], v[36:39], v[196:199], v[108:111]
	v_mfma_f32_16x16x32_bf16 v[108:111], v[152:155], v[200:203], v[108:111]
	v_mfma_f32_16x16x32_bf16 v[104:107], v[160:163], v[200:203], v[104:107]
	v_mfma_f32_16x16x32_bf16 v[104:107], v[156:159], v[196:199], v[104:107]
	v_mfma_f32_16x16x32_bf16 v[88:91], v[156:159], v[204:207], v[88:91]
	v_mfma_f32_16x16x32_bf16 v[88:91], v[160:163], v[208:211], v[88:91]
	v_mfma_f32_16x16x32_bf16 v[92:95], v[152:155], v[208:211], v[92:95]
	v_mfma_f32_16x16x32_bf16 v[92:95], v[36:39], v[204:207], v[92:95]
	s_setprio 0
	s_setprio 1
	v_mfma_f32_16x16x32_bf16 v[116:119], v[164:167], v[180:183], v[116:119]
	v_mfma_f32_16x16x32_bf16 v[116:119], v[168:171], v[184:187], v[116:119]
	v_mfma_f32_16x16x32_bf16 v[112:115], v[176:179], v[184:187], v[112:115]
	v_mfma_f32_16x16x32_bf16 v[112:115], v[172:175], v[180:183], v[112:115]
	v_mfma_f32_16x16x32_bf16 v[96:99], v[172:175], v[188:191], v[96:99]
	v_mfma_f32_16x16x32_bf16 v[96:99], v[176:179], v[192:195], v[96:99]
	v_mfma_f32_16x16x32_bf16 v[100:103], v[168:171], v[192:195], v[100:103]
	v_mfma_f32_16x16x32_bf16 v[100:103], v[164:167], v[188:191], v[100:103]
	v_mfma_f32_16x16x32_bf16 v[84:87], v[164:167], v[196:199], v[84:87]
	v_mfma_f32_16x16x32_bf16 v[84:87], v[168:171], v[200:203], v[84:87]
	v_mfma_f32_16x16x32_bf16 v[80:83], v[176:179], v[200:203], v[80:83]
	v_mfma_f32_16x16x32_bf16 v[80:83], v[172:175], v[196:199], v[80:83]
	v_mfma_f32_16x16x32_bf16 v[72:75], v[172:175], v[204:207], v[72:75]
	v_mfma_f32_16x16x32_bf16 v[72:75], v[176:179], v[208:211], v[72:75]
	v_mfma_f32_16x16x32_bf16 v[76:79], v[168:171], v[208:211], v[76:79]
	v_mfma_f32_16x16x32_bf16 v[76:79], v[164:167], v[204:207], v[76:79]
	s_setprio 0
	s_barrier
	s_add_i32 s68, s68, s34
	s_mov_b32 m0, s68
	ds_read_b128 v[180:183], v150 offset:16384
	ds_read_b128 v[184:187], v150 offset:17408
	ds_read_b128 v[188:191], v150 offset:18432
	ds_read_b128 v[192:195], v150 offset:19456
	ds_read_b128 v[196:199], v150 offset:20480
	ds_read_b128 v[200:203], v150 offset:21504
	ds_read_b128 v[204:207], v150 offset:22528
	ds_read_b128 v[208:211], v150 offset:23552
	global_load_lds_dwordx4 v138, s[26:27]
	s_add_i32 m0, s68, 0x2000
	s_add_u32 s68, s26, 0x4000
	s_addc_u32 s69, s27, 0
	s_add_i32 s88, s88, s34
	global_load_lds_dwordx4 v142, s[26:27]
	s_mov_b32 m0, s88
	s_nop 0
	global_load_lds_dwordx4 v138, s[68:69]
	s_add_i32 m0, s88, 0x2000
	s_nop 0
	global_load_lds_dwordx4 v142, s[68:69]
	s_mov_b32 m0, s9
	s_nop 0
	global_load_lds_dwordx4 v136, s[28:29]
	s_mov_b32 m0, s35
	s_nop 0
	global_load_lds_dwordx4 v140, s[28:29]
	s_waitcnt vmcnt(8)
	s_waitcnt lgkmcnt(0)
	v_mfma_f32_16x16x32_bf16 v[68:71], v[36:39], v[180:183], v[68:71]
	v_mfma_f32_16x16x32_bf16 v[68:71], v[152:155], v[184:187], v[68:71]
	v_mfma_f32_16x16x32_bf16 v[64:67], v[160:163], v[184:187], v[64:67]
	v_mfma_f32_16x16x32_bf16 v[64:67], v[156:159], v[180:183], v[64:67]
	s_barrier
; #define PG8_STAGE(bufoff, gbase, voff) do { _Pragma("unroll") for (int _i = 0; _i < 2; ++_i) \
;         __builtin_amdgcn_global_load_lds((const unsigned*)((const char*)(gbase) + (voff)[_i]), (PG8_LAS unsigned*)(lds + (bufoff) + ldsw + _i * 8192), 16, 0, 0); } while (0)
; #define PG8_LDA(dst, b, h) do { _Pragma("unroll") for (int m = 0; m < 4; ++m) _Pragma("unroll") for (int k = 0; k < 2; ++k) dst[m][k] = *(const PG8_LAS bf16x8*)(lds + PG8_SA(b, h) + aoff + m * 2048 + k * 1024); } while (0)
; #define PG8_LDB(dst, b, h) do { _Pragma("unroll") for (int n = 0; n < 2; ++n) _Pragma("unroll") for (int k = 0; k < 2; ++k) dst[n][k] = *(const PG8_LAS bf16x8*)(lds + PG8_SB(b, h) + boff + n * 2048 + k * 1024); } while (0)
; #define PG8_MMA(ai, bj, At, Bt) do { __builtin_amdgcn_s_setprio(1); _Pragma("unroll") for (int m = 0; m < 4; ++m) _Pragma("unroll") for (int n = 0; n < 2; ++n) _Pragma("unroll") for (int k = 0; k < 2; ++k) \
;         acc[ai][bj][m][n] = __builtin_amdgcn_mfma_f32_16x16x32_bf16(Bt[n][k], At[m][k], acc[ai][bj][m][n], 0, 0, 0); __builtin_amdgcn_s_setprio(0); } while (0)
; #define PG8_WAIT_V(n) asm volatile("s_waitcnt vmcnt(" #n ")" ::: "memory")
; #define PG8_WAIT_L(n) asm volatile("s_waitcnt lgkmcnt(" #n ")" ::: "memory")
; #define PG8_BAR __builtin_amdgcn_s_barrier()
; #define PG8_SCHED __builtin_amdgcn_sched_barrier(0)
; template <class Epi, class Sched, bool ALIGN_EPI = false, bool SP2 = false, bool ABLK = false, bool BBLK = false>
; __device__ __forceinline__ void gemm_phase(PG8_LAS unsigned char* lds, const Gemm g, const Sched& S, const Epi& E) {
;     ...
;             PG8_WAIT_V(8); PG8_WAIT_L(0); PG8_BAR; PG8_MMA(1, 0, At, B0); PG8_MMA(1, 1, At, B1); PG8_BAR; PG8_SCHED;
;             PG8_LDB(B0, 1, 0); PG8_LDB(B1, 1, 1); PG8_SCHED; PG8_LDA(At, 1, 0); PG8_STAGE(PG8_SA(0, 1), a2 + hstepA, voffA);
;             PG8_WAIT_V(8); PG8_WAIT_L(0); PG8_BAR; PG8_MMA(0, 0, At, B0); PG8_MMA(0, 1, At, B1); PG8_BAR; PG8_SCHED;
	s_setprio 1
	v_mfma_f32_16x16x32_bf16 v[56:59], v[156:159], v[188:191], v[56:59]
	v_mfma_f32_16x16x32_bf16 v[56:59], v[160:163], v[192:195], v[56:59]
	v_mfma_f32_16x16x32_bf16 v[60:63], v[152:155], v[192:195], v[60:63]
	v_mfma_f32_16x16x32_bf16 v[60:63], v[36:39], v[188:191], v[60:63]
	v_mfma_f32_16x16x32_bf16 v[44:47], v[36:39], v[196:199], v[44:47]
	v_mfma_f32_16x16x32_bf16 v[44:47], v[152:155], v[200:203], v[44:47]
	v_mfma_f32_16x16x32_bf16 v[40:43], v[160:163], v[200:203], v[40:43]
	v_mfma_f32_16x16x32_bf16 v[40:43], v[156:159], v[196:199], v[40:43]
	v_mfma_f32_16x16x32_bf16 v[20:23], v[156:159], v[204:207], v[20:23]
	v_mfma_f32_16x16x32_bf16 v[20:23], v[160:163], v[208:211], v[20:23]
	v_mfma_f32_16x16x32_bf16 v[24:27], v[152:155], v[208:211], v[24:27]
	v_mfma_f32_16x16x32_bf16 v[24:27], v[36:39], v[204:207], v[24:27]
	s_setprio 0
	s_setprio 1
	v_mfma_f32_16x16x32_bf16 v[48:51], v[172:175], v[180:183], v[48:51]
	v_mfma_f32_16x16x32_bf16 v[32:35], v[164:167], v[188:191], v[32:35]
	v_mfma_f32_16x16x32_bf16 v[28:31], v[172:175], v[188:191], v[28:31]
	v_mfma_f32_16x16x32_bf16 v[16:19], v[164:167], v[196:199], v[16:19]
	v_mfma_f32_16x16x32_bf16 v[12:15], v[172:175], v[196:199], v[12:15]
	v_mfma_f32_16x16x32_bf16 v[8:11], v[164:167], v[204:207], v[8:11]
	v_mfma_f32_16x16x32_bf16 v[4:7], v[172:175], v[204:207], v[4:7]
	v_mfma_f32_16x16x32_bf16 v[36:39], v[164:167], v[180:183], v[52:55]
	v_mfma_f32_16x16x32_bf16 v[48:51], v[176:179], v[184:187], v[48:51]
	v_mfma_f32_16x16x32_bf16 v[32:35], v[168:171], v[192:195], v[32:35]
	v_mfma_f32_16x16x32_bf16 v[28:31], v[176:179], v[192:195], v[28:31]
	v_mfma_f32_16x16x32_bf16 v[16:19], v[168:171], v[200:203], v[16:19]
	v_mfma_f32_16x16x32_bf16 v[12:15], v[176:179], v[200:203], v[12:15]
	v_mfma_f32_16x16x32_bf16 v[8:11], v[168:171], v[208:211], v[8:11]
	v_mfma_f32_16x16x32_bf16 v[4:7], v[176:179], v[208:211], v[4:7]
	v_mfma_f32_16x16x32_bf16 v[36:39], v[168:171], v[184:187], v[36:39]
	s_setprio 0
	s_barrier
	s_add_i32 s68, 0, 0x18000
	v_add_u32_e32 v151, s68, v148
	s_add_i32 s69, 0, 0x1c000
	ds_read_b128 v[52:55], v151
	ds_read_b128 v[152:155], v151 offset:1024
	ds_read_b128 v[156:159], v151 offset:2048
	ds_read_b128 v[160:163], v151 offset:3072
	v_add_u32_e32 v151, s69, v148
	ds_read_b128 v[164:167], v151
	ds_read_b128 v[168:171], v151 offset:1024
	ds_read_b128 v[172:175], v151 offset:2048
	ds_read_b128 v[176:179], v151 offset:3072
	s_add_u32 s28, s28, 0x4000
	s_addc_u32 s29, s29, 0
	s_mov_b32 m0, s36
	ds_read_b128 v[180:183], v150 offset:32768
	ds_read_b128 v[184:187], v150 offset:33792
	ds_read_b128 v[188:191], v150 offset:34816
	ds_read_b128 v[192:195], v150 offset:35840
	ds_read_b128 v[196:199], v150 offset:36864
	ds_read_b128 v[200:203], v150 offset:37888
	ds_read_b128 v[204:207], v150 offset:38912
	ds_read_b128 v[208:211], v150 offset:39936
	global_load_lds_dwordx4 v136, s[28:29]
	s_mov_b32 m0, s37
	s_nop 0
	global_load_lds_dwordx4 v140, s[28:29]
	s_waitcnt vmcnt(8)
	s_waitcnt lgkmcnt(0)
	v_mfma_f32_16x16x32_bf16 v[132:135], v[52:55], v[180:183], v[132:135]
	v_mfma_f32_16x16x32_bf16 v[132:135], v[152:155], v[184:187], v[132:135]
	v_mfma_f32_16x16x32_bf16 v[128:131], v[160:163], v[184:187], v[128:131]
	v_mfma_f32_16x16x32_bf16 v[128:131], v[156:159], v[180:183], v[128:131]
	s_barrier
	s_setprio 1
	v_mfma_f32_16x16x32_bf16 v[120:123], v[156:159], v[188:191], v[120:123]
	v_mfma_f32_16x16x32_bf16 v[120:123], v[160:163], v[192:195], v[120:123]
	v_mfma_f32_16x16x32_bf16 v[124:127], v[152:155], v[192:195], v[124:127]
	v_mfma_f32_16x16x32_bf16 v[124:127], v[52:55], v[188:191], v[124:127]
	v_mfma_f32_16x16x32_bf16 v[108:111], v[52:55], v[196:199], v[108:111]
	v_mfma_f32_16x16x32_bf16 v[108:111], v[152:155], v[200:203], v[108:111]
	v_mfma_f32_16x16x32_bf16 v[104:107], v[160:163], v[200:203], v[104:107]
	v_mfma_f32_16x16x32_bf16 v[104:107], v[156:159], v[196:199], v[104:107]
	v_mfma_f32_16x16x32_bf16 v[88:91], v[156:159], v[204:207], v[88:91]
	v_mfma_f32_16x16x32_bf16 v[88:91], v[160:163], v[208:211], v[88:91]
	v_mfma_f32_16x16x32_bf16 v[92:95], v[152:155], v[208:211], v[92:95]
	v_mfma_f32_16x16x32_bf16 v[92:95], v[52:55], v[204:207], v[92:95]
	s_setprio 0
	s_setprio 1
	v_mfma_f32_16x16x32_bf16 v[116:119], v[164:167], v[180:183], v[116:119]
	v_mfma_f32_16x16x32_bf16 v[116:119], v[168:171], v[184:187], v[116:119]
	v_mfma_f32_16x16x32_bf16 v[112:115], v[176:179], v[184:187], v[112:115]
	v_mfma_f32_16x16x32_bf16 v[112:115], v[172:175], v[180:183], v[112:115]
	v_mfma_f32_16x16x32_bf16 v[96:99], v[172:175], v[188:191], v[96:99]
	v_mfma_f32_16x16x32_bf16 v[96:99], v[176:179], v[192:195], v[96:99]
	v_mfma_f32_16x16x32_bf16 v[100:103], v[168:171], v[192:195], v[100:103]
	v_mfma_f32_16x16x32_bf16 v[100:103], v[164:167], v[188:191], v[100:103]
	v_mfma_f32_16x16x32_bf16 v[84:87], v[164:167], v[196:199], v[84:87]
	v_mfma_f32_16x16x32_bf16 v[84:87], v[168:171], v[200:203], v[84:87]
	v_mfma_f32_16x16x32_bf16 v[80:83], v[176:179], v[200:203], v[80:83]
	v_mfma_f32_16x16x32_bf16 v[80:83], v[172:175], v[196:199], v[80:83]
	v_mfma_f32_16x16x32_bf16 v[72:75], v[172:175], v[204:207], v[72:75]
	v_mfma_f32_16x16x32_bf16 v[72:75], v[176:179], v[208:211], v[72:75]
	v_mfma_f32_16x16x32_bf16 v[76:79], v[168:171], v[208:211], v[76:79]
	v_mfma_f32_16x16x32_bf16 v[76:79], v[164:167], v[204:207], v[76:79]
	s_setprio 0
	s_barrier
; #define PG8_STAGE(bufoff, gbase, voff) do { _Pragma("unroll") for (int _i = 0; _i < 2; ++_i) \
;         __builtin_amdgcn_global_load_lds((const unsigned*)((const char*)(gbase) + (voff)[_i]), (PG8_LAS unsigned*)(lds + (bufoff) + ldsw + _i * 8192), 16, 0, 0); } while (0)
; #define PG8_LDA(dst, b, h) do { _Pragma("unroll") for (int m = 0; m < 4; ++m) _Pragma("unroll") for (int k = 0; k < 2; ++k) dst[m][k] = *(const PG8_LAS bf16x8*)(lds + PG8_SA(b, h) + aoff + m * 2048 + k * 1024); } while (0)
; #define PG8_MMA(ai, bj, At, Bt) do { __builtin_amdgcn_s_setprio(1); _Pragma("unroll") for (int m = 0; m < 4; ++m) _Pragma("unroll") for (int n = 0; n < 2; ++n) _Pragma("unroll") for (int k = 0; k < 2; ++k) \
;         acc[ai][bj][m][n] = __builtin_amdgcn_mfma_f32_16x16x32_bf16(Bt[n][k], At[m][k], acc[ai][bj][m][n], 0, 0, 0); __builtin_amdgcn_s_setprio(0); } while (0)
; #define PG8_WAIT_V(n) asm volatile("s_waitcnt vmcnt(" #n ")" ::: "memory")
; #define PG8_WAIT_L(n) asm volatile("s_waitcnt lgkmcnt(" #n ")" ::: "memory")
; #define PG8_BAR __builtin_amdgcn_s_barrier()
; #define PG8_SCHED __builtin_amdgcn_sched_barrier(0)
; template <class Epi, class Sched, bool ALIGN_EPI = false, bool SP2 = false, bool ABLK = false, bool BBLK = false>
; __device__ __forceinline__ void gemm_phase(PG8_LAS unsigned char* lds, const Gemm g, const Sched& S, const Epi& E) {
;     ...
;             PG8_LDA(At, 1, 1); PG8_STAGE(PG8_SB(1, 0), b3, voffB); PG8_STAGE(PG8_SB(1, 1), b3 + hstepB, voffB); PG8_STAGE(PG8_SA(1, 0), a3, voffA);
;             PG8_WAIT_V(8); PG8_WAIT_L(0); PG8_BAR; PG8_MMA(1, 0, At, B0); PG8_MMA(1, 1, At, B1); PG8_BAR; PG8_SCHED;
;     ...
;         if constexpr (ALIGN_EPI) { if (wr == 0) PG8_BAR; }
	s_add_u32 s28, s26, 0x8000
	s_addc_u32 s29, s27, 0
	s_add_i32 s68, s68, s34
	s_mov_b32 m0, s68
	ds_read_b128 v[180:183], v150 offset:49152
	ds_read_b128 v[184:187], v150 offset:50176
	ds_read_b128 v[188:191], v150 offset:51200
	ds_read_b128 v[192:195], v150 offset:52224
	ds_read_b128 v[196:199], v150 offset:53248
	ds_read_b128 v[200:203], v150 offset:54272
	ds_read_b128 v[204:207], v150 offset:55296
	ds_read_b128 v[208:211], v150 offset:56320
	global_load_lds_dwordx4 v138, s[28:29]
	s_add_i32 m0, s68, 0x2000
	s_add_u32 s26, s26, 0xc000
	s_addc_u32 s27, s27, 0
	global_load_lds_dwordx4 v142, s[28:29]
	s_add_i32 s28, s69, s34
	s_mov_b32 m0, s28
	s_nop 0
	global_load_lds_dwordx4 v138, s[26:27]
	s_add_i32 m0, s28, 0x2000
	s_nop 0
	global_load_lds_dwordx4 v142, s[26:27]
	s_mov_b32 m0, s64
	s_nop 0
	global_load_lds_dwordx4 v136, s[24:25]
	s_mov_b32 m0, s65
	s_nop 0
	global_load_lds_dwordx4 v140, s[24:25]
	s_waitcnt vmcnt(8)
	s_waitcnt lgkmcnt(0)
	v_mfma_f32_16x16x32_bf16 v[68:71], v[52:55], v[180:183], v[68:71]
	v_mfma_f32_16x16x32_bf16 v[68:71], v[152:155], v[184:187], v[68:71]
	v_mfma_f32_16x16x32_bf16 v[64:67], v[160:163], v[184:187], v[64:67]
	v_mfma_f32_16x16x32_bf16 v[64:67], v[156:159], v[180:183], v[64:67]
	s_barrier
	s_setprio 1
	v_mfma_f32_16x16x32_bf16 v[56:59], v[156:159], v[188:191], v[56:59]
	v_mfma_f32_16x16x32_bf16 v[56:59], v[160:163], v[192:195], v[56:59]
	v_mfma_f32_16x16x32_bf16 v[60:63], v[152:155], v[192:195], v[60:63]
	v_mfma_f32_16x16x32_bf16 v[60:63], v[52:55], v[188:191], v[60:63]
	v_mfma_f32_16x16x32_bf16 v[44:47], v[52:55], v[196:199], v[44:47]
	v_mfma_f32_16x16x32_bf16 v[44:47], v[152:155], v[200:203], v[44:47]
	v_mfma_f32_16x16x32_bf16 v[40:43], v[160:163], v[200:203], v[40:43]
	v_mfma_f32_16x16x32_bf16 v[40:43], v[156:159], v[196:199], v[40:43]
	v_mfma_f32_16x16x32_bf16 v[20:23], v[156:159], v[204:207], v[20:23]
	v_mfma_f32_16x16x32_bf16 v[20:23], v[160:163], v[208:211], v[20:23]
	v_mfma_f32_16x16x32_bf16 v[24:27], v[152:155], v[208:211], v[24:27]
	v_mfma_f32_16x16x32_bf16 v[24:27], v[52:55], v[204:207], v[24:27]
	s_setprio 0
	s_setprio 1
	v_mfma_f32_16x16x32_bf16 v[36:39], v[164:167], v[180:183], v[36:39]
	v_mfma_f32_16x16x32_bf16 v[52:55], v[168:171], v[184:187], v[36:39]
	v_mfma_f32_16x16x32_bf16 v[36:39], v[172:175], v[180:183], v[48:51]
	v_mfma_f32_16x16x32_bf16 v[32:35], v[164:167], v[188:191], v[32:35]
	v_mfma_f32_16x16x32_bf16 v[28:31], v[172:175], v[188:191], v[28:31]
	v_mfma_f32_16x16x32_bf16 v[16:19], v[164:167], v[196:199], v[16:19]
	v_mfma_f32_16x16x32_bf16 v[12:15], v[172:175], v[196:199], v[12:15]
	v_mfma_f32_16x16x32_bf16 v[8:11], v[164:167], v[204:207], v[8:11]
	v_mfma_f32_16x16x32_bf16 v[4:7], v[172:175], v[204:207], v[4:7]
	v_mfma_f32_16x16x32_bf16 v[48:51], v[176:179], v[184:187], v[36:39]
	v_mfma_f32_16x16x32_bf16 v[32:35], v[168:171], v[192:195], v[32:35]
	v_mfma_f32_16x16x32_bf16 v[28:31], v[176:179], v[192:195], v[28:31]
	v_mfma_f32_16x16x32_bf16 v[16:19], v[168:171], v[200:203], v[16:19]
	v_mfma_f32_16x16x32_bf16 v[12:15], v[176:179], v[200:203], v[12:15]
	v_mfma_f32_16x16x32_bf16 v[8:11], v[168:171], v[208:211], v[8:11]
	v_mfma_f32_16x16x32_bf16 v[4:7], v[176:179], v[208:211], v[4:7]
	s_setprio 0
	s_barrier
	s_add_i32 s13, s13, 2
	s_add_u32 s22, s22, 0x10000
	s_addc_u32 s23, s23, 0
	s_add_u32 s82, s82, 0x10000
	s_addc_u32 vcc_lo, vcc_lo, 0
	s_cmp_gt_u32 s13, 29
	s_cbranch_scc0 .LBB0_2111
	s_and_b64 vcc, exec, s[6:7]
	s_movk_i32 s77, 0x1000
	s_cbranch_vccz .LBB0_2114
	s_barrier
